# K tensors stored tile-chunk-major so each K LDS-DMA piece is a contiguous 1 KiB (in-proj epilogue store addresses + attention K source offsets)
# speedup vs baseline: 1.0166x; 1.0042x over previous
;     __device__ __forceinline__ void operator()(const pg8::f32x4 (&acc)[2][2][4][2], const pg8::Unit& u, int wr, int wc, int fr, int fq) const {
;     ...
;         pg8::f32x4 gg[2][2];
; #pragma unroll
;         for (int bj = 0; bj < 2; ++bj)
; #pragma unroll
;             for (int n = 0; n < 2; ++n) gg[bj][n] = *(const pg8::f32x4*)(gain + 32 * bj + 8 * fq + 4 * n);
; #pragma unroll
;         for (int ai = 0; ai < 2; ++ai)
; #pragma unroll
;             for (int m = 0; m < 4; ++m) {
;                 const int r = u.pm * 256 + ai * 128 + wr * 64 + m * 16 + fr;
;                 const bool lat = r < ML; int b, t; if (lat) { b = r >> 13; t = r & 8191; } else { b = (r - ML) >> 8; t = (r - ML) & 255; }
;                 const size_t drow = keyrow ? (size_t)(b * nh + hidx) * NKEY + (lat ? 256 + t : t) : (size_t)r;
.LBB0_301:
	s_cmp_lg_u64 s[44:45], 0
	s_cselect_b32 s100, 0x70, 0
	s_cmp_eq_u32 s94, 64
	s_cselect_b32 s100, s100, 0
	v_mov_b32_e32 v246, s100
	v_mul_u32_u24_e32 v246, 36, v246
	v_mov_b32_e32 v247, 0
	v_lshlrev_b32_e32 v52, 2, v152
	global_load_dwordx4 v[56:59], v52, s[92:93] offset:16
	global_load_dwordx4 v[60:63], v52, s[92:93]
	global_load_dwordx4 v[48:51], v52, s[92:93] offset:144
	s_nop 0
	global_load_dwordx4 v[52:55], v52, s[92:93] offset:128
	s_lshl_b32 s70, s40, 8
	s_add_i32 s70, s70, s60
	s_xor_b64 s[92:93], s[66:67], -1
	v_or_b32_e32 v162, s70, v153
	s_mov_b64 s[4:5], -1
	v_cmp_gt_i32_e64 s[40:41], s97, v162
	s_and_b64 vcc, exec, s[92:93]
	s_cbranch_vccz .LBB0_303
	v_ashrrev_i32_e32 v163, 31, v162
	s_mov_b64 s[4:5], 0

;     __device__ __forceinline__ void operator()(const pg8::f32x4 (&acc)[2][2][4][2], const pg8::Unit& u, int wr, int wc, int fr, int fq) const {
;     ...
;                 bf16_t* dp = dbase + drow * dpitch + dcol + 8 * fq;
;                 float rinv = 1.f;
;                 if (normed) { float ss = 0.f;
; #pragma unroll
;                     for (int bj = 0; bj < 2; ++bj)
; #pragma unroll
;                         for (int n = 0; n < 2; ++n) { const pg8::f32x4 x = acc[ai][bj][m][n]; ss += (x[0] * x[0] + x[1] * x[1]) + (x[2] * x[2] + x[3] * x[3]); }
;                     ss = xrow_sum(ss);
;                     rinv = scale * __builtin_amdgcn_rsqf(ss * (1.0f / 64.0f) + EPSF); }
.LBB0_305:
	s_add_i32 s4, s38, -2
	s_cmp_gt_u32 s4, 2
	s_cselect_b64 s[66:67], -1, 0
	s_ashr_i32 s43, s42, 31
	s_lshl_b64 s[4:5], s[42:43], 1
	s_add_u32 s4, s14, s4
	s_addc_u32 s5, s15, s5
	v_cndmask_b32_e64 v164, 0, 1, s[44:45]
	v_lshl_add_u64 v[160:161], s[4:5], 0, v[208:209]
	v_mbcnt_lo_u32_b32 v244, -1, 0
	v_mbcnt_hi_u32_b32 v244, -1, v244
	v_lshrrev_b32_e32 v244, 4, v244
	v_mul_u32_u24_e32 v244, 9, v244
	v_mul_u32_u24_e32 v244, s100, v244
	v_mov_b32_e32 v245, 0
	v_lshl_add_u64 v[160:161], v[160:161], 0, v[244:245]
	s_mov_b64 s[4:5], -1
	s_and_b64 vcc, exec, s[66:67]
	v_cmp_ne_u32_e64 s[38:39], 1, v164
	s_cbranch_vccz .LBB0_317
	s_and_b64 vcc, exec, s[38:39]
	v_mov_b32_e32 v164, 1.0
	s_cbranch_vccnz .LBB0_308
	v_mul_f32_e32 v164, v141, v141
	v_mul_f32_e32 v165, v143, v143
	v_fmac_f32_e32 v164, v140, v140
	v_fmac_f32_e32 v165, v142, v142
	v_add_f32_e32 v164, v164, v165
	v_mul_f32_e32 v165, v137, v137
	v_mul_f32_e32 v166, v139, v139
	v_fmac_f32_e32 v165, v136, v136
	v_fmac_f32_e32 v166, v138, v138
	v_add_f32_e32 v165, v165, v166
	v_add_f32_e32 v164, v164, v165
	v_mul_f32_e32 v165, v133, v133
	v_mul_f32_e32 v166, v135, v135
	v_fmac_f32_e32 v165, v132, v132
	v_fmac_f32_e32 v166, v134, v134
	v_add_f32_e32 v165, v165, v166
	v_add_f32_e32 v164, v164, v165
	v_mul_f32_e32 v165, v129, v129
	v_mul_f32_e32 v166, v131, v131
	v_fmac_f32_e32 v165, v128, v128
	v_fmac_f32_e32 v166, v130, v130
	v_add_f32_e32 v165, v165, v166
	v_add_f32_e32 v164, v164, v165
	v_mov_b32_e32 v165, v164
	s_nop 1
	v_permlane16_swap_b32_e32 v164, v165
	v_add_f32_e32 v164, v164, v165
	v_mov_b32_e32 v165, v164
	s_nop 1
	v_permlane32_swap_b32_e32 v164, v165
	v_add_f32_e32 v164, v164, v165
	v_fmamk_f32 v164, v164, 0x3c800000, v220
	v_rsq_f32_e32 v164, v164
	s_nop 0
	v_mul_f32_e32 v164, s73, v164

; __device__ __forceinline__ unsigned pk2(float lo, float hi) { const f32x2_cv v = {lo, hi}; const bf16x2_cv b = __builtin_convertvector(v, bf16x2_cv); return __builtin_bit_cast(unsigned, b); }
;     __device__ __forceinline__ void operator()(const pg8::f32x4 (&acc)[2][2][4][2], const pg8::Unit& u, int wr, int wc, int fr, int fq) const {
;     ...
;                 for (int bj = 0; bj < 2; ++bj) {
;                     pg8::f32x4 y0 = acc[ai][bj][m][0], y1 = acc[ai][bj][m][1];
;                     if (normed) {
;                         y0 = y0 * rinv * gg[bj][0]; y1 = y1 * rinv * gg[bj][1];
;                         if (lat) { const int p = bj == 0 ? (t >> 6) : (t & 63); const pg8::f32x4* rp = (const pg8::f32x4*)(rope + p * 16 + 4 * fq); const pg8::f32x4 c01 = rp[0], c23 = rp[1];
;                             const pg8::f32x4 z0 = {y0[0] * c01[0] - y0[1] * c01[1], y0[0] * c01[1] + y0[1] * c01[0], y0[2] * c01[2] - y0[3] * c01[3], y0[2] * c01[3] + y0[3] * c01[2]};
;                             const pg8::f32x4 z1 = {y1[0] * c23[0] - y1[1] * c23[1], y1[0] * c23[1] + y1[1] * c23[0], y1[2] * c23[2] - y1[3] * c23[3], y1[2] * c23[3] + y1[3] * c23[2]};
;                             y0 = z0; y1 = z1; }
;                     }
;                     v4u o; o.x = pk2(y0[0], y0[1]); o.y = pk2(y0[2], y0[3]); o.z = pk2(y1[0], y1[1]); o.w = pk2(y1[2], y1[3]);
;                     *(v4u*)(dp + 32 * bj) = o;
.LBB0_312:
	v_and_b32_e32 v245, 63, v162
	v_mul_lo_u32 v174, v163, s94
	v_mul_lo_u32 v175, v162, s95
	v_mad_u64_u32 v[162:163], s[4:5], v162, s94, 0
	v_add3_u32 v163, v163, v175, v174
	v_lshl_add_u64 v[162:163], v[162:163], 1, v[160:161]
	v_mul_u32_u24_e32 v244, s100, v245
	v_sub_u32_e32 v244, 0, v244
	v_ashrrev_i32_e32 v245, 31, v244
	v_lshl_add_u64 v[162:163], v[162:163], 0, v[244:245]
	v_cvt_pk_bf16_f32 v166, v166, v167
	v_cvt_pk_bf16_f32 v167, v172, v173
	v_cvt_pk_bf16_f32 v168, v168, v169
	v_cvt_pk_bf16_f32 v169, v170, v171
	flat_store_dwordx4 v[162:163], v[166:169]
	s_and_b64 vcc, exec, s[38:39]
	v_mov_b32_e32 v172, v134
	v_mov_b32_e32 v166, v132
	v_mov_b32_e32 v167, v133
	v_mov_b32_e32 v173, v135
	v_mov_b32_e32 v168, v128
	v_mov_b32_e32 v169, v129
	v_mov_b32_e32 v170, v130
	v_mov_b32_e32 v171, v131
	s_cbranch_vccnz .LBB0_316
	v_mov_b32_e32 v168, v164
	v_mov_b32_e32 v169, v164
	v_pk_mul_f32 v[166:167], v[134:135], v[168:169]
	v_pk_mul_f32 v[170:171], v[132:133], v[164:165]
	v_pk_mul_f32 v[168:169], v[130:131], v[168:169]
	v_pk_mul_f32 v[164:165], v[128:129], v[164:165]
	s_waitcnt vmcnt(0)
	v_pk_mul_f32 v[172:173], v[54:55], v[166:167]
	v_pk_mul_f32 v[166:167], v[52:53], v[170:171]
	v_pk_mul_f32 v[170:171], v[50:51], v[168:169]
	v_pk_mul_f32 v[168:169], v[48:49], v[164:165]
	s_and_saveexec_b64 s[4:5], s[40:41]
	s_cbranch_execz .LBB0_315
	v_lshlrev_b32_e32 v164, 7, v202
	v_and_b32_e32 v164, 0x780, v164
	v_mov_b32_e32 v165, v209
	v_lshl_add_u64 v[164:165], v[154:155], 0, v[164:165]
	flat_load_dwordx4 v[174:177], v[164:165]
	flat_load_dwordx4 v[178:181], v[164:165] offset:16
	s_waitcnt vmcnt(0) lgkmcnt(0)
	v_pk_mul_f32 v[182:183], v[166:167], v[174:175] op_sel:[1,1] op_sel_hi:[1,0]
	v_pk_mul_f32 v[164:165], v[166:167], v[174:175]
	v_pk_fma_f32 v[166:167], v[166:167], v[174:175], v[182:183] op_sel_hi:[0,1,1]
	v_mul_f32_e32 v166, v173, v177
	v_pk_fma_f32 v[174:175], v[172:173], v[176:177], v[166:167] op_sel_hi:[1,1,0] neg_lo:[0,0,1] neg_hi:[0,0,1]
	v_mul_f32_e32 v166, v173, v176
	v_pk_fma_f32 v[172:173], v[172:173], v[176:177], v[166:167] op_sel:[0,1,0] op_sel_hi:[1,0,0]
	v_pk_mul_f32 v[184:185], v[168:169], v[178:179] op_sel:[1,1] op_sel_hi:[1,0]
	v_mul_f32_e32 v166, v171, v181
	v_pk_mul_f32 v[176:177], v[168:169], v[178:179]
	v_pk_fma_f32 v[168:169], v[168:169], v[178:179], v[184:185] op_sel_hi:[0,1,1]
	v_pk_fma_f32 v[178:179], v[170:171], v[180:181], v[166:167] op_sel_hi:[1,1,0] neg_lo:[0,0,1] neg_hi:[0,0,1]
	v_mul_f32_e32 v166, v171, v180
	v_pk_fma_f32 v[170:171], v[170:171], v[180:181], v[166:167] op_sel:[0,1,0] op_sel_hi:[1,0,0]
	v_sub_f32_e32 v166, v164, v182
	v_sub_f32_e32 v168, v176, v184
	v_mov_b32_e32 v171, v170
	v_mov_b32_e32 v170, v178
	v_mov_b32_e32 v173, v172
	v_mov_b32_e32 v172, v174

; __device__ __forceinline__ unsigned pk2(float lo, float hi) { const f32x2_cv v = {lo, hi}; const bf16x2_cv b = __builtin_convertvector(v, bf16x2_cv); return __builtin_bit_cast(unsigned, b); }
;     __device__ __forceinline__ void operator()(const pg8::f32x4 (&acc)[2][2][4][2], const pg8::Unit& u, int wr, int wc, int fr, int fq) const {
;     ...
;                     v4u o; o.x = pk2(y0[0], y0[1]); o.y = pk2(y0[2], y0[3]); o.z = pk2(y1[0], y1[1]); o.w = pk2(y1[2], y1[3]);
;                     *(v4u*)(dp + 32 * bj) = o;
.LBB0_316:
	v_cvt_pk_bf16_f32 v164, v166, v167
	v_cvt_pk_bf16_f32 v165, v172, v173
	v_cvt_pk_bf16_f32 v166, v168, v169
	v_cvt_pk_bf16_f32 v167, v170, v171
	s_mov_b64 s[4:5], 0
	v_lshl_add_u64 v[162:163], v[162:163], 0, v[246:247]
	flat_store_dwordx4 v[162:163], v[164:167] offset:64

; __device__ __forceinline__ unsigned pk2(float lo, float hi) { const f32x2_cv v = {lo, hi}; const bf16x2_cv b = __builtin_convertvector(v, bf16x2_cv); return __builtin_bit_cast(unsigned, b); }
;     __device__ __forceinline__ void operator()(const pg8::f32x4 (&acc)[2][2][4][2], const pg8::Unit& u, int wr, int wc, int fr, int fq) const {
;     ...
;                 for (int bj = 0; bj < 2; ++bj) {
;                     pg8::f32x4 y0 = acc[ai][bj][m][0], y1 = acc[ai][bj][m][1];
;                     if (normed) {
;                         y0 = y0 * rinv * gg[bj][0]; y1 = y1 * rinv * gg[bj][1];
;                         if (lat) { const int p = bj == 0 ? (t >> 6) : (t & 63); const pg8::f32x4* rp = (const pg8::f32x4*)(rope + p * 16 + 4 * fq); const pg8::f32x4 c01 = rp[0], c23 = rp[1];
;                             const pg8::f32x4 z0 = {y0[0] * c01[0] - y0[1] * c01[1], y0[0] * c01[1] + y0[1] * c01[0], y0[2] * c01[2] - y0[3] * c01[3], y0[2] * c01[3] + y0[3] * c01[2]};
;                             const pg8::f32x4 z1 = {y1[0] * c23[0] - y1[1] * c23[1], y1[0] * c23[1] + y1[1] * c23[0], y1[2] * c23[2] - y1[3] * c23[3], y1[2] * c23[3] + y1[3] * c23[2]};
;                             y0 = z0; y1 = z1; }
;                     }
;                     v4u o; o.x = pk2(y0[0], y0[1]); o.y = pk2(y0[2], y0[3]); o.z = pk2(y1[0], y1[1]); o.w = pk2(y1[2], y1[3]);
;                     *(v4u*)(dp + 32 * bj) = o;
.LBB0_330:
	v_and_b32_e32 v245, 63, v128
	v_mul_lo_u32 v142, v129, s94
	v_mul_lo_u32 v143, v128, s95
	v_mad_u64_u32 v[128:129], s[4:5], v128, s94, 0
	v_add3_u32 v129, v129, v143, v142
	v_lshl_add_u64 v[128:129], v[128:129], 1, v[160:161]
	v_mul_u32_u24_e32 v244, s100, v245
	v_sub_u32_e32 v244, 0, v244
	v_ashrrev_i32_e32 v245, 31, v244
	v_lshl_add_u64 v[128:129], v[128:129], 0, v[244:245]
	v_cvt_pk_bf16_f32 v132, v132, v133
	v_cvt_pk_bf16_f32 v133, v138, v139
	v_cvt_pk_bf16_f32 v134, v134, v135
	v_cvt_pk_bf16_f32 v135, v136, v137
	flat_store_dwordx4 v[128:129], v[132:135]
	s_and_b64 vcc, exec, s[38:39]
	v_mov_b32_e32 v138, v118
	v_mov_b32_e32 v132, v116
	v_mov_b32_e32 v133, v117
	v_mov_b32_e32 v139, v119
	v_mov_b32_e32 v134, v112
	v_mov_b32_e32 v135, v113
	v_mov_b32_e32 v136, v114
	v_mov_b32_e32 v137, v115
	s_cbranch_vccnz .LBB0_334
	v_mov_b32_e32 v134, v130
	v_mov_b32_e32 v135, v130
	v_pk_mul_f32 v[132:133], v[118:119], v[134:135]
	v_pk_mul_f32 v[136:137], v[116:117], v[130:131]
	v_pk_mul_f32 v[134:135], v[114:115], v[134:135]
	v_pk_mul_f32 v[130:131], v[112:113], v[130:131]
	s_waitcnt vmcnt(0)
	v_pk_mul_f32 v[138:139], v[54:55], v[132:133]
	v_pk_mul_f32 v[132:133], v[52:53], v[136:137]
	v_pk_mul_f32 v[136:137], v[50:51], v[134:135]
	v_pk_mul_f32 v[134:135], v[48:49], v[130:131]
	s_and_saveexec_b64 s[4:5], s[44:45]
	s_cbranch_execz .LBB0_333
	v_lshlrev_b32_e32 v130, 7, v141
	v_and_b32_e32 v130, 0xf80, v130
	v_mov_b32_e32 v131, v209
	v_lshl_add_u64 v[130:131], v[154:155], 0, v[130:131]
	flat_load_dwordx4 v[202:205], v[130:131]
	flat_load_dwordx4 v[210:213], v[130:131] offset:16
	s_waitcnt vmcnt(0) lgkmcnt(0)
	v_pk_mul_f32 v[142:143], v[132:133], v[202:203] op_sel:[1,1] op_sel_hi:[1,0]
	v_pk_mul_f32 v[130:131], v[132:133], v[202:203]
	v_pk_fma_f32 v[132:133], v[132:133], v[202:203], v[142:143] op_sel_hi:[0,1,1]
	v_mul_f32_e32 v132, v139, v205
	v_pk_fma_f32 v[202:203], v[138:139], v[204:205], v[132:133] op_sel_hi:[1,1,0] neg_lo:[0,0,1] neg_hi:[0,0,1]
	v_mul_f32_e32 v132, v139, v204
	v_pk_fma_f32 v[138:139], v[138:139], v[204:205], v[132:133] op_sel:[0,1,0] op_sel_hi:[1,0,0]
	v_pk_mul_f32 v[206:207], v[134:135], v[210:211] op_sel:[1,1] op_sel_hi:[1,0]
	v_mul_f32_e32 v132, v137, v213
	v_pk_mul_f32 v[204:205], v[134:135], v[210:211]
	v_pk_fma_f32 v[134:135], v[134:135], v[210:211], v[206:207] op_sel_hi:[0,1,1]
	v_pk_fma_f32 v[210:211], v[136:137], v[212:213], v[132:133] op_sel_hi:[1,1,0] neg_lo:[0,0,1] neg_hi:[0,0,1]
	v_mul_f32_e32 v132, v137, v212
	v_pk_fma_f32 v[136:137], v[136:137], v[212:213], v[132:133] op_sel:[0,1,0] op_sel_hi:[1,0,0]
	v_sub_f32_e32 v132, v130, v142
	v_sub_f32_e32 v134, v204, v206
	v_mov_b32_e32 v137, v136
	v_mov_b32_e32 v136, v210
	v_mov_b32_e32 v139, v138
	v_mov_b32_e32 v138, v202

; __device__ __forceinline__ unsigned pk2(float lo, float hi) { const f32x2_cv v = {lo, hi}; const bf16x2_cv b = __builtin_convertvector(v, bf16x2_cv); return __builtin_bit_cast(unsigned, b); }
;     __device__ __forceinline__ void operator()(const pg8::f32x4 (&acc)[2][2][4][2], const pg8::Unit& u, int wr, int wc, int fr, int fq) const {
;     ...
;                     v4u o; o.x = pk2(y0[0], y0[1]); o.y = pk2(y0[2], y0[3]); o.z = pk2(y1[0], y1[1]); o.w = pk2(y1[2], y1[3]);
;                     *(v4u*)(dp + 32 * bj) = o;
.LBB0_334:
	v_cvt_pk_bf16_f32 v130, v132, v133
	v_cvt_pk_bf16_f32 v131, v138, v139
	v_cvt_pk_bf16_f32 v132, v134, v135
	v_cvt_pk_bf16_f32 v133, v136, v137
	s_mov_b64 s[4:5], 0
	v_lshl_add_u64 v[128:129], v[128:129], 0, v[246:247]
	flat_store_dwordx4 v[128:129], v[130:133] offset:64

; __device__ __forceinline__ unsigned pk2(float lo, float hi) { const f32x2_cv v = {lo, hi}; const bf16x2_cv b = __builtin_convertvector(v, bf16x2_cv); return __builtin_bit_cast(unsigned, b); }
;     __device__ __forceinline__ void operator()(const pg8::f32x4 (&acc)[2][2][4][2], const pg8::Unit& u, int wr, int wc, int fr, int fq) const {
;     ...
;                 for (int bj = 0; bj < 2; ++bj) {
;                     pg8::f32x4 y0 = acc[ai][bj][m][0], y1 = acc[ai][bj][m][1];
;                     if (normed) {
;                         y0 = y0 * rinv * gg[bj][0]; y1 = y1 * rinv * gg[bj][1];
;                         if (lat) { const int p = bj == 0 ? (t >> 6) : (t & 63); const pg8::f32x4* rp = (const pg8::f32x4*)(rope + p * 16 + 4 * fq); const pg8::f32x4 c01 = rp[0], c23 = rp[1];
;                             const pg8::f32x4 z0 = {y0[0] * c01[0] - y0[1] * c01[1], y0[0] * c01[1] + y0[1] * c01[0], y0[2] * c01[2] - y0[3] * c01[3], y0[2] * c01[3] + y0[3] * c01[2]};
;                             const pg8::f32x4 z1 = {y1[0] * c23[0] - y1[1] * c23[1], y1[0] * c23[1] + y1[1] * c23[0], y1[2] * c23[2] - y1[3] * c23[3], y1[2] * c23[3] + y1[3] * c23[2]};
;                             y0 = z0; y1 = z1; }
;                     }
;                     v4u o; o.x = pk2(y0[0], y0[1]); o.y = pk2(y0[2], y0[3]); o.z = pk2(y1[0], y1[1]); o.w = pk2(y1[2], y1[3]);
;                     *(v4u*)(dp + 32 * bj) = o;
.LBB0_383:
	v_and_b32_e32 v245, 63, v112
	v_mul_lo_u32 v126, v113, s94
	v_mul_lo_u32 v127, v112, s95
	v_mad_u64_u32 v[112:113], s[4:5], v112, s94, 0
	v_add3_u32 v113, v113, v127, v126
	v_lshl_add_u64 v[112:113], v[112:113], 1, v[160:161]
	v_mul_u32_u24_e32 v244, s100, v245
	v_sub_u32_e32 v244, 0, v244
	v_ashrrev_i32_e32 v245, 31, v244
	v_lshl_add_u64 v[112:113], v[112:113], 0, v[244:245]
	v_cvt_pk_bf16_f32 v116, v116, v117
	v_cvt_pk_bf16_f32 v117, v122, v123
	v_cvt_pk_bf16_f32 v118, v118, v119
	v_cvt_pk_bf16_f32 v119, v120, v121
	flat_store_dwordx4 v[112:113], v[116:119]
	s_and_b64 vcc, exec, s[38:39]
	v_mov_b32_e32 v122, v102
	v_mov_b32_e32 v116, v100
	v_mov_b32_e32 v117, v101
	v_mov_b32_e32 v123, v103
	v_mov_b32_e32 v118, v96
	v_mov_b32_e32 v119, v97
	v_mov_b32_e32 v120, v98
	v_mov_b32_e32 v121, v99
	s_cbranch_vccnz .LBB0_387
	v_mov_b32_e32 v118, v114
	v_mov_b32_e32 v119, v114
	v_pk_mul_f32 v[116:117], v[102:103], v[118:119]
	v_pk_mul_f32 v[120:121], v[100:101], v[114:115]
	v_pk_mul_f32 v[118:119], v[98:99], v[118:119]
	v_pk_mul_f32 v[114:115], v[96:97], v[114:115]
	s_waitcnt vmcnt(0)
	v_pk_mul_f32 v[122:123], v[54:55], v[116:117]
	v_pk_mul_f32 v[116:117], v[52:53], v[120:121]
	v_pk_mul_f32 v[120:121], v[50:51], v[118:119]
	v_pk_mul_f32 v[118:119], v[48:49], v[114:115]
	s_and_saveexec_b64 s[4:5], s[44:45]
	s_cbranch_execz .LBB0_386
	v_lshlrev_b32_e32 v114, 7, v125
	v_and_b32_e32 v114, 0x1780, v114
	v_mov_b32_e32 v115, v209
	v_lshl_add_u64 v[114:115], v[154:155], 0, v[114:115]
	flat_load_dwordx4 v[126:129], v[114:115]
	flat_load_dwordx4 v[130:133], v[114:115] offset:16
	s_waitcnt vmcnt(0) lgkmcnt(0)
	v_pk_mul_f32 v[134:135], v[116:117], v[126:127] op_sel:[1,1] op_sel_hi:[1,0]
	v_pk_mul_f32 v[114:115], v[116:117], v[126:127]
	v_pk_fma_f32 v[116:117], v[116:117], v[126:127], v[134:135] op_sel_hi:[0,1,1]
	v_mul_f32_e32 v116, v123, v129
	v_pk_fma_f32 v[126:127], v[122:123], v[128:129], v[116:117] op_sel_hi:[1,1,0] neg_lo:[0,0,1] neg_hi:[0,0,1]
	v_mul_f32_e32 v116, v123, v128
	v_pk_fma_f32 v[122:123], v[122:123], v[128:129], v[116:117] op_sel:[0,1,0] op_sel_hi:[1,0,0]
	v_pk_mul_f32 v[136:137], v[118:119], v[130:131] op_sel:[1,1] op_sel_hi:[1,0]
	v_mul_f32_e32 v116, v121, v133
	v_pk_mul_f32 v[128:129], v[118:119], v[130:131]
	v_pk_fma_f32 v[118:119], v[118:119], v[130:131], v[136:137] op_sel_hi:[0,1,1]
	v_pk_fma_f32 v[130:131], v[120:121], v[132:133], v[116:117] op_sel_hi:[1,1,0] neg_lo:[0,0,1] neg_hi:[0,0,1]
	v_mul_f32_e32 v116, v121, v132
	v_pk_fma_f32 v[120:121], v[120:121], v[132:133], v[116:117] op_sel:[0,1,0] op_sel_hi:[1,0,0]
	v_sub_f32_e32 v116, v114, v134
	v_sub_f32_e32 v118, v128, v136
	v_mov_b32_e32 v121, v120
	v_mov_b32_e32 v120, v130
	v_mov_b32_e32 v123, v122
	v_mov_b32_e32 v122, v126

; __device__ __forceinline__ unsigned pk2(float lo, float hi) { const f32x2_cv v = {lo, hi}; const bf16x2_cv b = __builtin_convertvector(v, bf16x2_cv); return __builtin_bit_cast(unsigned, b); }
;     __device__ __forceinline__ void operator()(const pg8::f32x4 (&acc)[2][2][4][2], const pg8::Unit& u, int wr, int wc, int fr, int fq) const {
;     ...
;                     v4u o; o.x = pk2(y0[0], y0[1]); o.y = pk2(y0[2], y0[3]); o.z = pk2(y1[0], y1[1]); o.w = pk2(y1[2], y1[3]);
;                     *(v4u*)(dp + 32 * bj) = o;
.LBB0_387:
	v_cvt_pk_bf16_f32 v114, v116, v117
	v_cvt_pk_bf16_f32 v115, v122, v123
	v_cvt_pk_bf16_f32 v116, v118, v119
	v_cvt_pk_bf16_f32 v117, v120, v121
	v_lshl_add_u64 v[112:113], v[112:113], 0, v[246:247]
	flat_store_dwordx4 v[112:113], v[114:117] offset:64
	s_branch .LBB0_343

; __device__ __forceinline__ unsigned pk2(float lo, float hi) { const f32x2_cv v = {lo, hi}; const bf16x2_cv b = __builtin_convertvector(v, bf16x2_cv); return __builtin_bit_cast(unsigned, b); }
;     __device__ __forceinline__ void operator()(const pg8::f32x4 (&acc)[2][2][4][2], const pg8::Unit& u, int wr, int wc, int fr, int fq) const {
;     ...
;                 for (int bj = 0; bj < 2; ++bj) {
;                     pg8::f32x4 y0 = acc[ai][bj][m][0], y1 = acc[ai][bj][m][1];
;                     if (normed) {
;                         y0 = y0 * rinv * gg[bj][0]; y1 = y1 * rinv * gg[bj][1];
;                         if (lat) { const int p = bj == 0 ? (t >> 6) : (t & 63); const pg8::f32x4* rp = (const pg8::f32x4*)(rope + p * 16 + 4 * fq); const pg8::f32x4 c01 = rp[0], c23 = rp[1];
;                             const pg8::f32x4 z0 = {y0[0] * c01[0] - y0[1] * c01[1], y0[0] * c01[1] + y0[1] * c01[0], y0[2] * c01[2] - y0[3] * c01[3], y0[2] * c01[3] + y0[3] * c01[2]};
;                             const pg8::f32x4 z1 = {y1[0] * c23[0] - y1[1] * c23[1], y1[0] * c23[1] + y1[1] * c23[0], y1[2] * c23[2] - y1[3] * c23[3], y1[2] * c23[3] + y1[3] * c23[2]};
;                             y0 = z0; y1 = z1; }
;                     }
;                     v4u o; o.x = pk2(y0[0], y0[1]); o.y = pk2(y0[2], y0[3]); o.z = pk2(y1[0], y1[1]); o.w = pk2(y1[2], y1[3]);
;                     *(v4u*)(dp + 32 * bj) = o;
.LBB0_395:
	v_and_b32_e32 v245, 63, v96
	v_mul_lo_u32 v110, v97, s94
	v_mul_lo_u32 v111, v96, s95
	v_mad_u64_u32 v[96:97], s[4:5], v96, s94, 0
	v_add3_u32 v97, v97, v111, v110
	v_lshl_add_u64 v[96:97], v[96:97], 1, v[160:161]
	v_mul_u32_u24_e32 v244, s100, v245
	v_sub_u32_e32 v244, 0, v244
	v_ashrrev_i32_e32 v245, 31, v244
	v_lshl_add_u64 v[96:97], v[96:97], 0, v[244:245]
	v_cvt_pk_bf16_f32 v100, v100, v101
	v_cvt_pk_bf16_f32 v101, v106, v107
	v_cvt_pk_bf16_f32 v102, v102, v103
	v_cvt_pk_bf16_f32 v103, v104, v105
	flat_store_dwordx4 v[96:97], v[100:103]
	s_and_b64 vcc, exec, s[38:39]
	v_mov_b32_e32 v106, v86
	v_mov_b32_e32 v100, v84
	v_mov_b32_e32 v101, v85
	v_mov_b32_e32 v107, v87
	v_mov_b32_e32 v102, v80
	v_mov_b32_e32 v103, v81
	v_mov_b32_e32 v104, v82
	v_mov_b32_e32 v105, v83
	s_cbranch_vccnz .LBB0_399
	v_mov_b32_e32 v102, v98
	v_mov_b32_e32 v103, v98
	v_pk_mul_f32 v[100:101], v[86:87], v[102:103]
	v_pk_mul_f32 v[104:105], v[84:85], v[98:99]
	v_pk_mul_f32 v[102:103], v[82:83], v[102:103]
	v_pk_mul_f32 v[98:99], v[80:81], v[98:99]
	s_waitcnt vmcnt(0)
	v_pk_mul_f32 v[106:107], v[54:55], v[100:101]
	v_pk_mul_f32 v[100:101], v[52:53], v[104:105]
	v_pk_mul_f32 v[104:105], v[50:51], v[102:103]
	v_pk_mul_f32 v[102:103], v[48:49], v[98:99]
	s_and_saveexec_b64 s[4:5], s[44:45]
	s_cbranch_execz .LBB0_398
	v_lshlrev_b32_e32 v98, 7, v109
	v_and_b32_e32 v98, 0x1f80, v98
	v_mov_b32_e32 v99, v209
	v_lshl_add_u64 v[98:99], v[154:155], 0, v[98:99]
	flat_load_dwordx4 v[110:113], v[98:99]
	flat_load_dwordx4 v[114:117], v[98:99] offset:16
	s_waitcnt vmcnt(0) lgkmcnt(0)
	v_pk_mul_f32 v[118:119], v[100:101], v[110:111] op_sel:[1,1] op_sel_hi:[1,0]
	v_pk_mul_f32 v[98:99], v[100:101], v[110:111]
	v_pk_fma_f32 v[100:101], v[100:101], v[110:111], v[118:119] op_sel_hi:[0,1,1]
	v_mul_f32_e32 v100, v107, v113
	v_pk_fma_f32 v[110:111], v[106:107], v[112:113], v[100:101] op_sel_hi:[1,1,0] neg_lo:[0,0,1] neg_hi:[0,0,1]
	v_mul_f32_e32 v100, v107, v112
	v_pk_fma_f32 v[106:107], v[106:107], v[112:113], v[100:101] op_sel:[0,1,0] op_sel_hi:[1,0,0]
	v_pk_mul_f32 v[120:121], v[102:103], v[114:115] op_sel:[1,1] op_sel_hi:[1,0]
	v_mul_f32_e32 v100, v105, v117
	v_pk_mul_f32 v[112:113], v[102:103], v[114:115]
	v_pk_fma_f32 v[102:103], v[102:103], v[114:115], v[120:121] op_sel_hi:[0,1,1]
	v_pk_fma_f32 v[114:115], v[104:105], v[116:117], v[100:101] op_sel_hi:[1,1,0] neg_lo:[0,0,1] neg_hi:[0,0,1]
	v_mul_f32_e32 v100, v105, v116
	v_pk_fma_f32 v[104:105], v[104:105], v[116:117], v[100:101] op_sel:[0,1,0] op_sel_hi:[1,0,0]
	v_sub_f32_e32 v100, v98, v118
	v_sub_f32_e32 v102, v112, v120
	v_mov_b32_e32 v105, v104
	v_mov_b32_e32 v104, v114
	v_mov_b32_e32 v107, v106
	v_mov_b32_e32 v106, v110

; __device__ __forceinline__ unsigned pk2(float lo, float hi) { const f32x2_cv v = {lo, hi}; const bf16x2_cv b = __builtin_convertvector(v, bf16x2_cv); return __builtin_bit_cast(unsigned, b); }
;     __device__ __forceinline__ void operator()(const pg8::f32x4 (&acc)[2][2][4][2], const pg8::Unit& u, int wr, int wc, int fr, int fq) const {
;     ...
;                     v4u o; o.x = pk2(y0[0], y0[1]); o.y = pk2(y0[2], y0[3]); o.z = pk2(y1[0], y1[1]); o.w = pk2(y1[2], y1[3]);
;                     *(v4u*)(dp + 32 * bj) = o;
.LBB0_399:
	v_cvt_pk_bf16_f32 v98, v100, v101
	v_cvt_pk_bf16_f32 v99, v106, v107
	v_cvt_pk_bf16_f32 v100, v102, v103
	v_cvt_pk_bf16_f32 v101, v104, v105
	v_lshl_add_u64 v[96:97], v[96:97], 0, v[246:247]
	flat_store_dwordx4 v[96:97], v[98:101] offset:64
	s_branch .LBB0_349

; __device__ __forceinline__ unsigned pk2(float lo, float hi) { const f32x2_cv v = {lo, hi}; const bf16x2_cv b = __builtin_convertvector(v, bf16x2_cv); return __builtin_bit_cast(unsigned, b); }
;     __device__ __forceinline__ void operator()(const pg8::f32x4 (&acc)[2][2][4][2], const pg8::Unit& u, int wr, int wc, int fr, int fq) const {
;     ...
;                 for (int bj = 0; bj < 2; ++bj) {
;                     pg8::f32x4 y0 = acc[ai][bj][m][0], y1 = acc[ai][bj][m][1];
;                     if (normed) {
;                         y0 = y0 * rinv * gg[bj][0]; y1 = y1 * rinv * gg[bj][1];
;                         if (lat) { const int p = bj == 0 ? (t >> 6) : (t & 63); const pg8::f32x4* rp = (const pg8::f32x4*)(rope + p * 16 + 4 * fq); const pg8::f32x4 c01 = rp[0], c23 = rp[1];
;                             const pg8::f32x4 z0 = {y0[0] * c01[0] - y0[1] * c01[1], y0[0] * c01[1] + y0[1] * c01[0], y0[2] * c01[2] - y0[3] * c01[3], y0[2] * c01[3] + y0[3] * c01[2]};
;                             const pg8::f32x4 z1 = {y1[0] * c23[0] - y1[1] * c23[1], y1[0] * c23[1] + y1[1] * c23[0], y1[2] * c23[2] - y1[3] * c23[3], y1[2] * c23[3] + y1[3] * c23[2]};
;                             y0 = z0; y1 = z1; }
;                     }
;                     v4u o; o.x = pk2(y0[0], y0[1]); o.y = pk2(y0[2], y0[3]); o.z = pk2(y1[0], y1[1]); o.w = pk2(y1[2], y1[3]);
;                     *(v4u*)(dp + 32 * bj) = o;
.LBB0_407:
	v_and_b32_e32 v245, 63, v80
	v_mul_lo_u32 v94, v81, s94
	v_mul_lo_u32 v95, v80, s95
	v_mad_u64_u32 v[80:81], s[4:5], v80, s94, 0
	v_add3_u32 v81, v81, v95, v94
	v_lshl_add_u64 v[80:81], v[80:81], 1, v[160:161]
	v_mul_u32_u24_e32 v244, s100, v245
	v_sub_u32_e32 v244, 0, v244
	v_ashrrev_i32_e32 v245, 31, v244
	v_lshl_add_u64 v[80:81], v[80:81], 0, v[244:245]
	v_cvt_pk_bf16_f32 v84, v84, v85
	v_cvt_pk_bf16_f32 v85, v90, v91
	v_cvt_pk_bf16_f32 v86, v86, v87
	v_cvt_pk_bf16_f32 v87, v88, v89
	flat_store_dwordx4 v[80:81], v[84:87]
	s_and_b64 vcc, exec, s[38:39]
	v_mov_b32_e32 v90, v70
	v_mov_b32_e32 v84, v68
	v_mov_b32_e32 v85, v69
	v_mov_b32_e32 v91, v71
	v_mov_b32_e32 v86, v64
	v_mov_b32_e32 v87, v65
	v_mov_b32_e32 v88, v66
	v_mov_b32_e32 v89, v67
	s_cbranch_vccnz .LBB0_411
	v_mov_b32_e32 v86, v82
	v_mov_b32_e32 v87, v82
	v_pk_mul_f32 v[84:85], v[70:71], v[86:87]
	v_pk_mul_f32 v[88:89], v[68:69], v[82:83]
	v_pk_mul_f32 v[86:87], v[66:67], v[86:87]
	v_pk_mul_f32 v[82:83], v[64:65], v[82:83]
	s_waitcnt vmcnt(0)
	v_pk_mul_f32 v[90:91], v[54:55], v[84:85]
	v_pk_mul_f32 v[84:85], v[52:53], v[88:89]
	v_pk_mul_f32 v[88:89], v[50:51], v[86:87]
	v_pk_mul_f32 v[86:87], v[48:49], v[82:83]
	s_and_saveexec_b64 s[4:5], s[44:45]
	s_cbranch_execz .LBB0_410
	v_lshlrev_b32_e32 v82, 7, v93
	v_and_b32_e32 v82, 0x780, v82
	v_mov_b32_e32 v83, v209
	v_lshl_add_u64 v[82:83], v[154:155], 0, v[82:83]
	flat_load_dwordx4 v[94:97], v[82:83]
	flat_load_dwordx4 v[98:101], v[82:83] offset:16
	s_waitcnt vmcnt(0) lgkmcnt(0)
	v_pk_mul_f32 v[102:103], v[84:85], v[94:95] op_sel:[1,1] op_sel_hi:[1,0]
	v_pk_mul_f32 v[82:83], v[84:85], v[94:95]
	v_pk_fma_f32 v[84:85], v[84:85], v[94:95], v[102:103] op_sel_hi:[0,1,1]
	v_mul_f32_e32 v84, v91, v97
	v_pk_fma_f32 v[94:95], v[90:91], v[96:97], v[84:85] op_sel_hi:[1,1,0] neg_lo:[0,0,1] neg_hi:[0,0,1]
	v_mul_f32_e32 v84, v91, v96
	v_pk_fma_f32 v[90:91], v[90:91], v[96:97], v[84:85] op_sel:[0,1,0] op_sel_hi:[1,0,0]
	v_pk_mul_f32 v[104:105], v[86:87], v[98:99] op_sel:[1,1] op_sel_hi:[1,0]
	v_mul_f32_e32 v84, v89, v101
	v_pk_mul_f32 v[96:97], v[86:87], v[98:99]
	v_pk_fma_f32 v[86:87], v[86:87], v[98:99], v[104:105] op_sel_hi:[0,1,1]
	v_pk_fma_f32 v[98:99], v[88:89], v[100:101], v[84:85] op_sel_hi:[1,1,0] neg_lo:[0,0,1] neg_hi:[0,0,1]
	v_mul_f32_e32 v84, v89, v100
	v_pk_fma_f32 v[88:89], v[88:89], v[100:101], v[84:85] op_sel:[0,1,0] op_sel_hi:[1,0,0]
	v_sub_f32_e32 v84, v82, v102
	v_sub_f32_e32 v86, v96, v104
	v_mov_b32_e32 v89, v88
	v_mov_b32_e32 v88, v98
	v_mov_b32_e32 v91, v90
	v_mov_b32_e32 v90, v94

; __device__ __forceinline__ unsigned pk2(float lo, float hi) { const f32x2_cv v = {lo, hi}; const bf16x2_cv b = __builtin_convertvector(v, bf16x2_cv); return __builtin_bit_cast(unsigned, b); }
;     __device__ __forceinline__ void operator()(const pg8::f32x4 (&acc)[2][2][4][2], const pg8::Unit& u, int wr, int wc, int fr, int fq) const {
;     ...
;                     v4u o; o.x = pk2(y0[0], y0[1]); o.y = pk2(y0[2], y0[3]); o.z = pk2(y1[0], y1[1]); o.w = pk2(y1[2], y1[3]);
;                     *(v4u*)(dp + 32 * bj) = o;
.LBB0_411:
	v_cvt_pk_bf16_f32 v82, v84, v85
	v_cvt_pk_bf16_f32 v83, v90, v91
	v_cvt_pk_bf16_f32 v84, v86, v87
	v_cvt_pk_bf16_f32 v85, v88, v89
	v_lshl_add_u64 v[80:81], v[80:81], 0, v[246:247]
	flat_store_dwordx4 v[80:81], v[82:85] offset:64
	s_branch .LBB0_355

; __device__ __forceinline__ unsigned pk2(float lo, float hi) { const f32x2_cv v = {lo, hi}; const bf16x2_cv b = __builtin_convertvector(v, bf16x2_cv); return __builtin_bit_cast(unsigned, b); }
;     __device__ __forceinline__ void operator()(const pg8::f32x4 (&acc)[2][2][4][2], const pg8::Unit& u, int wr, int wc, int fr, int fq) const {
;     ...
;                 for (int bj = 0; bj < 2; ++bj) {
;                     pg8::f32x4 y0 = acc[ai][bj][m][0], y1 = acc[ai][bj][m][1];
;                     if (normed) {
;                         y0 = y0 * rinv * gg[bj][0]; y1 = y1 * rinv * gg[bj][1];
;                         if (lat) { const int p = bj == 0 ? (t >> 6) : (t & 63); const pg8::f32x4* rp = (const pg8::f32x4*)(rope + p * 16 + 4 * fq); const pg8::f32x4 c01 = rp[0], c23 = rp[1];
;                             const pg8::f32x4 z0 = {y0[0] * c01[0] - y0[1] * c01[1], y0[0] * c01[1] + y0[1] * c01[0], y0[2] * c01[2] - y0[3] * c01[3], y0[2] * c01[3] + y0[3] * c01[2]};
;                             const pg8::f32x4 z1 = {y1[0] * c23[0] - y1[1] * c23[1], y1[0] * c23[1] + y1[1] * c23[0], y1[2] * c23[2] - y1[3] * c23[3], y1[2] * c23[3] + y1[3] * c23[2]};
;                             y0 = z0; y1 = z1; }
;                     }
;                     v4u o; o.x = pk2(y0[0], y0[1]); o.y = pk2(y0[2], y0[3]); o.z = pk2(y1[0], y1[1]); o.w = pk2(y1[2], y1[3]);
;                     *(v4u*)(dp + 32 * bj) = o;
.LBB0_419:
	v_and_b32_e32 v245, 63, v64
	v_mul_lo_u32 v78, v65, s94
	v_mul_lo_u32 v79, v64, s95
	v_mad_u64_u32 v[64:65], s[4:5], v64, s94, 0
	v_add3_u32 v65, v65, v79, v78
	v_lshl_add_u64 v[64:65], v[64:65], 1, v[160:161]
	v_mul_u32_u24_e32 v244, s100, v245
	v_sub_u32_e32 v244, 0, v244
	v_ashrrev_i32_e32 v245, 31, v244
	v_lshl_add_u64 v[64:65], v[64:65], 0, v[244:245]
	v_cvt_pk_bf16_f32 v68, v68, v69
	v_cvt_pk_bf16_f32 v69, v74, v75
	v_cvt_pk_bf16_f32 v70, v70, v71
	v_cvt_pk_bf16_f32 v71, v72, v73
	flat_store_dwordx4 v[64:65], v[68:71]
	s_and_b64 vcc, exec, s[38:39]
	v_mov_b32_e32 v74, v38
	v_mov_b32_e32 v68, v36
	v_mov_b32_e32 v69, v37
	v_mov_b32_e32 v75, v39
	v_mov_b32_e32 v70, v32
	v_mov_b32_e32 v71, v33
	v_mov_b32_e32 v72, v34
	v_mov_b32_e32 v73, v35
	s_cbranch_vccnz .LBB0_423
	v_mov_b32_e32 v70, v66
	v_mov_b32_e32 v71, v66
	v_pk_mul_f32 v[68:69], v[38:39], v[70:71]
	v_pk_mul_f32 v[72:73], v[36:37], v[66:67]
	v_pk_mul_f32 v[70:71], v[34:35], v[70:71]
	v_pk_mul_f32 v[66:67], v[32:33], v[66:67]
	s_waitcnt vmcnt(0)
	v_pk_mul_f32 v[74:75], v[54:55], v[68:69]
	v_pk_mul_f32 v[68:69], v[52:53], v[72:73]
	v_pk_mul_f32 v[72:73], v[50:51], v[70:71]
	v_pk_mul_f32 v[70:71], v[48:49], v[66:67]
	s_and_saveexec_b64 s[4:5], s[44:45]
	s_cbranch_execz .LBB0_422
	v_lshlrev_b32_e32 v66, 7, v77
	v_and_b32_e32 v66, 0xf80, v66
	v_mov_b32_e32 v67, v209
	v_lshl_add_u64 v[66:67], v[154:155], 0, v[66:67]
	flat_load_dwordx4 v[78:81], v[66:67]
	flat_load_dwordx4 v[82:85], v[66:67] offset:16
	s_waitcnt vmcnt(0) lgkmcnt(0)
	v_pk_mul_f32 v[86:87], v[68:69], v[78:79] op_sel:[1,1] op_sel_hi:[1,0]
	v_pk_mul_f32 v[66:67], v[68:69], v[78:79]
	v_pk_fma_f32 v[68:69], v[68:69], v[78:79], v[86:87] op_sel_hi:[0,1,1]
	v_mul_f32_e32 v68, v75, v81
	v_pk_fma_f32 v[78:79], v[74:75], v[80:81], v[68:69] op_sel_hi:[1,1,0] neg_lo:[0,0,1] neg_hi:[0,0,1]
	v_mul_f32_e32 v68, v75, v80
	v_pk_fma_f32 v[74:75], v[74:75], v[80:81], v[68:69] op_sel:[0,1,0] op_sel_hi:[1,0,0]
	v_pk_mul_f32 v[88:89], v[70:71], v[82:83] op_sel:[1,1] op_sel_hi:[1,0]
	v_mul_f32_e32 v68, v73, v85
	v_pk_mul_f32 v[80:81], v[70:71], v[82:83]
	v_pk_fma_f32 v[70:71], v[70:71], v[82:83], v[88:89] op_sel_hi:[0,1,1]
	v_pk_fma_f32 v[82:83], v[72:73], v[84:85], v[68:69] op_sel_hi:[1,1,0] neg_lo:[0,0,1] neg_hi:[0,0,1]
	v_mul_f32_e32 v68, v73, v84
	v_pk_fma_f32 v[72:73], v[72:73], v[84:85], v[68:69] op_sel:[0,1,0] op_sel_hi:[1,0,0]
	v_sub_f32_e32 v68, v66, v86
	v_sub_f32_e32 v70, v80, v88
	v_mov_b32_e32 v73, v72
	v_mov_b32_e32 v72, v82
	v_mov_b32_e32 v75, v74
	v_mov_b32_e32 v74, v78

; __device__ __forceinline__ unsigned pk2(float lo, float hi) { const f32x2_cv v = {lo, hi}; const bf16x2_cv b = __builtin_convertvector(v, bf16x2_cv); return __builtin_bit_cast(unsigned, b); }
;     __device__ __forceinline__ void operator()(const pg8::f32x4 (&acc)[2][2][4][2], const pg8::Unit& u, int wr, int wc, int fr, int fq) const {
;     ...
;                     v4u o; o.x = pk2(y0[0], y0[1]); o.y = pk2(y0[2], y0[3]); o.z = pk2(y1[0], y1[1]); o.w = pk2(y1[2], y1[3]);
;                     *(v4u*)(dp + 32 * bj) = o;
.LBB0_423:
	v_cvt_pk_bf16_f32 v66, v68, v69
	v_cvt_pk_bf16_f32 v67, v74, v75
	v_cvt_pk_bf16_f32 v68, v70, v71
	v_cvt_pk_bf16_f32 v69, v72, v73
	v_lshl_add_u64 v[64:65], v[64:65], 0, v[246:247]
	flat_store_dwordx4 v[64:65], v[66:69] offset:64
	s_branch .LBB0_361

; __device__ __forceinline__ unsigned pk2(float lo, float hi) { const f32x2_cv v = {lo, hi}; const bf16x2_cv b = __builtin_convertvector(v, bf16x2_cv); return __builtin_bit_cast(unsigned, b); }
;     __device__ __forceinline__ void operator()(const pg8::f32x4 (&acc)[2][2][4][2], const pg8::Unit& u, int wr, int wc, int fr, int fq) const {
;     ...
;                 for (int bj = 0; bj < 2; ++bj) {
;                     pg8::f32x4 y0 = acc[ai][bj][m][0], y1 = acc[ai][bj][m][1];
;                     if (normed) {
;                         y0 = y0 * rinv * gg[bj][0]; y1 = y1 * rinv * gg[bj][1];
;                         if (lat) { const int p = bj == 0 ? (t >> 6) : (t & 63); const pg8::f32x4* rp = (const pg8::f32x4*)(rope + p * 16 + 4 * fq); const pg8::f32x4 c01 = rp[0], c23 = rp[1];
;                             const pg8::f32x4 z0 = {y0[0] * c01[0] - y0[1] * c01[1], y0[0] * c01[1] + y0[1] * c01[0], y0[2] * c01[2] - y0[3] * c01[3], y0[2] * c01[3] + y0[3] * c01[2]};
;                             const pg8::f32x4 z1 = {y1[0] * c23[0] - y1[1] * c23[1], y1[0] * c23[1] + y1[1] * c23[0], y1[2] * c23[2] - y1[3] * c23[3], y1[2] * c23[3] + y1[3] * c23[2]};
;                             y0 = z0; y1 = z1; }
;                     }
;                     v4u o; o.x = pk2(y0[0], y0[1]); o.y = pk2(y0[2], y0[3]); o.z = pk2(y1[0], y1[1]); o.w = pk2(y1[2], y1[3]);
;                     *(v4u*)(dp + 32 * bj) = o;
.LBB0_431:
	v_and_b32_e32 v245, 63, v32
	v_mul_lo_u32 v46, v33, s94
	v_mul_lo_u32 v47, v32, s95
	v_mad_u64_u32 v[32:33], s[4:5], v32, s94, 0
	v_add3_u32 v33, v33, v47, v46
	v_lshl_add_u64 v[32:33], v[32:33], 1, v[160:161]
	v_mul_u32_u24_e32 v244, s100, v245
	v_sub_u32_e32 v244, 0, v244
	v_ashrrev_i32_e32 v245, 31, v244
	v_lshl_add_u64 v[32:33], v[32:33], 0, v[244:245]
	v_cvt_pk_bf16_f32 v36, v36, v37
	v_cvt_pk_bf16_f32 v37, v42, v43
	v_cvt_pk_bf16_f32 v38, v38, v39
	v_cvt_pk_bf16_f32 v39, v40, v41
	flat_store_dwordx4 v[32:33], v[36:39]
	s_and_b64 vcc, exec, s[38:39]
	v_mov_b32_e32 v42, v22
	v_mov_b32_e32 v36, v20
	v_mov_b32_e32 v37, v21
	v_mov_b32_e32 v43, v23
	v_mov_b32_e32 v38, v16
	v_mov_b32_e32 v39, v17
	v_mov_b32_e32 v40, v18
	v_mov_b32_e32 v41, v19
	s_cbranch_vccnz .LBB0_435
	v_mov_b32_e32 v38, v34
	v_mov_b32_e32 v39, v34
	v_pk_mul_f32 v[36:37], v[22:23], v[38:39]
	v_pk_mul_f32 v[40:41], v[20:21], v[34:35]
	v_pk_mul_f32 v[38:39], v[18:19], v[38:39]
	v_pk_mul_f32 v[34:35], v[16:17], v[34:35]
	s_waitcnt vmcnt(0)
	v_pk_mul_f32 v[42:43], v[54:55], v[36:37]
	v_pk_mul_f32 v[36:37], v[52:53], v[40:41]
	v_pk_mul_f32 v[40:41], v[50:51], v[38:39]
	v_pk_mul_f32 v[38:39], v[48:49], v[34:35]
	s_and_saveexec_b64 s[4:5], s[44:45]
	s_cbranch_execz .LBB0_434
	v_lshlrev_b32_e32 v34, 7, v45
	v_and_b32_e32 v34, 0x1780, v34
	v_mov_b32_e32 v35, v209
	v_lshl_add_u64 v[34:35], v[154:155], 0, v[34:35]
	flat_load_dwordx4 v[64:67], v[34:35]
	flat_load_dwordx4 v[68:71], v[34:35] offset:16
	s_waitcnt vmcnt(0) lgkmcnt(0)
	v_pk_mul_f32 v[46:47], v[36:37], v[64:65] op_sel:[1,1] op_sel_hi:[1,0]
	v_pk_mul_f32 v[34:35], v[36:37], v[64:65]
	v_pk_fma_f32 v[36:37], v[36:37], v[64:65], v[46:47] op_sel_hi:[0,1,1]
	v_mul_f32_e32 v36, v43, v67
	v_pk_fma_f32 v[64:65], v[42:43], v[66:67], v[36:37] op_sel_hi:[1,1,0] neg_lo:[0,0,1] neg_hi:[0,0,1]
	v_mul_f32_e32 v36, v43, v66
	v_pk_fma_f32 v[42:43], v[42:43], v[66:67], v[36:37] op_sel:[0,1,0] op_sel_hi:[1,0,0]
	v_pk_mul_f32 v[72:73], v[38:39], v[68:69] op_sel:[1,1] op_sel_hi:[1,0]
	v_mul_f32_e32 v36, v41, v71
	v_pk_mul_f32 v[66:67], v[38:39], v[68:69]
	v_pk_fma_f32 v[38:39], v[38:39], v[68:69], v[72:73] op_sel_hi:[0,1,1]
	v_pk_fma_f32 v[68:69], v[40:41], v[70:71], v[36:37] op_sel_hi:[1,1,0] neg_lo:[0,0,1] neg_hi:[0,0,1]
	v_mul_f32_e32 v36, v41, v70
	v_pk_fma_f32 v[40:41], v[40:41], v[70:71], v[36:37] op_sel:[0,1,0] op_sel_hi:[1,0,0]
	v_sub_f32_e32 v36, v34, v46
	v_sub_f32_e32 v38, v66, v72
	v_mov_b32_e32 v41, v40
	v_mov_b32_e32 v40, v68
	v_mov_b32_e32 v43, v42
	v_mov_b32_e32 v42, v64

; __device__ __forceinline__ unsigned pk2(float lo, float hi) { const f32x2_cv v = {lo, hi}; const bf16x2_cv b = __builtin_convertvector(v, bf16x2_cv); return __builtin_bit_cast(unsigned, b); }
;     __device__ __forceinline__ void operator()(const pg8::f32x4 (&acc)[2][2][4][2], const pg8::Unit& u, int wr, int wc, int fr, int fq) const {
;     ...
;                     v4u o; o.x = pk2(y0[0], y0[1]); o.y = pk2(y0[2], y0[3]); o.z = pk2(y1[0], y1[1]); o.w = pk2(y1[2], y1[3]);
;                     *(v4u*)(dp + 32 * bj) = o;
.LBB0_435:
	v_cvt_pk_bf16_f32 v34, v36, v37
	v_cvt_pk_bf16_f32 v35, v42, v43
	v_cvt_pk_bf16_f32 v36, v38, v39
	v_cvt_pk_bf16_f32 v37, v40, v41
	v_lshl_add_u64 v[32:33], v[32:33], 0, v[246:247]
	flat_store_dwordx4 v[32:33], v[34:37] offset:64
	s_branch .LBB0_367

; __device__ __forceinline__ unsigned pk2(float lo, float hi) { const f32x2_cv v = {lo, hi}; const bf16x2_cv b = __builtin_convertvector(v, bf16x2_cv); return __builtin_bit_cast(unsigned, b); }
;     __device__ __forceinline__ void operator()(const pg8::f32x4 (&acc)[2][2][4][2], const pg8::Unit& u, int wr, int wc, int fr, int fq) const {
;     ...
;                 for (int bj = 0; bj < 2; ++bj) {
;                     pg8::f32x4 y0 = acc[ai][bj][m][0], y1 = acc[ai][bj][m][1];
;                     if (normed) {
;                         y0 = y0 * rinv * gg[bj][0]; y1 = y1 * rinv * gg[bj][1];
;                         if (lat) { const int p = bj == 0 ? (t >> 6) : (t & 63); const pg8::f32x4* rp = (const pg8::f32x4*)(rope + p * 16 + 4 * fq); const pg8::f32x4 c01 = rp[0], c23 = rp[1];
;                             const pg8::f32x4 z0 = {y0[0] * c01[0] - y0[1] * c01[1], y0[0] * c01[1] + y0[1] * c01[0], y0[2] * c01[2] - y0[3] * c01[3], y0[2] * c01[3] + y0[3] * c01[2]};
;                             const pg8::f32x4 z1 = {y1[0] * c23[0] - y1[1] * c23[1], y1[0] * c23[1] + y1[1] * c23[0], y1[2] * c23[2] - y1[3] * c23[3], y1[2] * c23[3] + y1[3] * c23[2]};
;                             y0 = z0; y1 = z1; }
;                     }
;                     v4u o; o.x = pk2(y0[0], y0[1]); o.y = pk2(y0[2], y0[3]); o.z = pk2(y1[0], y1[1]); o.w = pk2(y1[2], y1[3]);
;                     *(v4u*)(dp + 32 * bj) = o;
.LBB0_443:
	v_and_b32_e32 v245, 63, v16
	v_mul_lo_u32 v30, v17, s94
	v_mul_lo_u32 v31, v16, s95
	v_mad_u64_u32 v[16:17], s[4:5], v16, s94, 0
	v_add3_u32 v17, v17, v31, v30
	v_lshl_add_u64 v[16:17], v[16:17], 1, v[160:161]
	v_mul_u32_u24_e32 v244, s100, v245
	v_sub_u32_e32 v244, 0, v244
	v_ashrrev_i32_e32 v245, 31, v244
	v_lshl_add_u64 v[16:17], v[16:17], 0, v[244:245]
	v_cvt_pk_bf16_f32 v20, v20, v21
	v_cvt_pk_bf16_f32 v21, v26, v27
	v_cvt_pk_bf16_f32 v22, v22, v23
	v_cvt_pk_bf16_f32 v23, v24, v25
	flat_store_dwordx4 v[16:17], v[20:23]
	s_and_b64 vcc, exec, s[38:39]
	v_mov_b32_e32 v26, v6
	v_mov_b32_e32 v20, v4
	v_mov_b32_e32 v21, v5
	v_mov_b32_e32 v27, v7
	v_mov_b32_e32 v22, v0
	v_mov_b32_e32 v23, v1
	v_mov_b32_e32 v24, v2
	v_mov_b32_e32 v25, v3
	s_cbranch_vccnz .LBB0_447
	v_mov_b32_e32 v22, v18
	v_mov_b32_e32 v23, v18
	v_pk_mul_f32 v[20:21], v[6:7], v[22:23]
	v_pk_mul_f32 v[24:25], v[4:5], v[18:19]
	v_pk_mul_f32 v[22:23], v[2:3], v[22:23]
	v_pk_mul_f32 v[18:19], v[0:1], v[18:19]
	s_waitcnt vmcnt(0)
	v_pk_mul_f32 v[26:27], v[54:55], v[20:21]
	v_pk_mul_f32 v[20:21], v[52:53], v[24:25]
	v_pk_mul_f32 v[24:25], v[50:51], v[22:23]
	v_pk_mul_f32 v[22:23], v[48:49], v[18:19]
	s_and_saveexec_b64 s[4:5], s[44:45]
	s_cbranch_execz .LBB0_446
	v_lshlrev_b32_e32 v18, 7, v29
	v_and_b32_e32 v18, 0x1f80, v18
	v_mov_b32_e32 v19, v209
	v_lshl_add_u64 v[18:19], v[154:155], 0, v[18:19]
	flat_load_dwordx4 v[30:33], v[18:19]
	flat_load_dwordx4 v[34:37], v[18:19] offset:16
	s_waitcnt vmcnt(0) lgkmcnt(0)
	v_pk_mul_f32 v[38:39], v[20:21], v[30:31] op_sel:[1,1] op_sel_hi:[1,0]
	v_pk_mul_f32 v[18:19], v[20:21], v[30:31]
	v_pk_fma_f32 v[20:21], v[20:21], v[30:31], v[38:39] op_sel_hi:[0,1,1]
	v_mul_f32_e32 v20, v27, v33
	v_pk_fma_f32 v[30:31], v[26:27], v[32:33], v[20:21] op_sel_hi:[1,1,0] neg_lo:[0,0,1] neg_hi:[0,0,1]
	v_mul_f32_e32 v20, v27, v32
	v_pk_fma_f32 v[26:27], v[26:27], v[32:33], v[20:21] op_sel:[0,1,0] op_sel_hi:[1,0,0]
	v_pk_mul_f32 v[40:41], v[22:23], v[34:35] op_sel:[1,1] op_sel_hi:[1,0]
	v_mul_f32_e32 v20, v25, v37
	v_pk_mul_f32 v[32:33], v[22:23], v[34:35]
	v_pk_fma_f32 v[22:23], v[22:23], v[34:35], v[40:41] op_sel_hi:[0,1,1]
	v_pk_fma_f32 v[34:35], v[24:25], v[36:37], v[20:21] op_sel_hi:[1,1,0] neg_lo:[0,0,1] neg_hi:[0,0,1]
	v_mul_f32_e32 v20, v25, v36
	v_pk_fma_f32 v[24:25], v[24:25], v[36:37], v[20:21] op_sel:[0,1,0] op_sel_hi:[1,0,0]
	v_sub_f32_e32 v20, v18, v38
	v_sub_f32_e32 v22, v32, v40
	v_mov_b32_e32 v25, v24
	v_mov_b32_e32 v24, v34
	v_mov_b32_e32 v27, v26
	v_mov_b32_e32 v26, v30

; __device__ __forceinline__ unsigned pk2(float lo, float hi) { const f32x2_cv v = {lo, hi}; const bf16x2_cv b = __builtin_convertvector(v, bf16x2_cv); return __builtin_bit_cast(unsigned, b); }
;     __device__ __forceinline__ void operator()(const pg8::f32x4 (&acc)[2][2][4][2], const pg8::Unit& u, int wr, int wc, int fr, int fq) const {
;     ...
;                     v4u o; o.x = pk2(y0[0], y0[1]); o.y = pk2(y0[2], y0[3]); o.z = pk2(y1[0], y1[1]); o.w = pk2(y1[2], y1[3]);
;                     *(v4u*)(dp + 32 * bj) = o;
.LBB0_447:
	v_cvt_pk_bf16_f32 v18, v20, v21
	v_cvt_pk_bf16_f32 v19, v26, v27
	v_cvt_pk_bf16_f32 v20, v22, v23
	v_cvt_pk_bf16_f32 v21, v24, v25
	v_lshl_add_u64 v[16:17], v[16:17], 0, v[246:247]
	flat_store_dwordx4 v[16:17], v[18:21] offset:64
	s_branch .LBB0_373

; __device__ __forceinline__ int lane_id_v() { int l; asm volatile("v_mbcnt_lo_u32_b32 %0, -1, 0\n\tv_mbcnt_hi_u32_b32 %0, -1, %0" : "=v"(l)); return l; }
;   #define DMA_K(t,slot) glds16(ksrc+(long)(t)*KVBLK*PK,(unsigned)__builtin_amdgcn_readfirstlane(kdst+(slot)))
;   #define DMA_V(t,slot) do{ glds16(vsrc+(long)(t)*KVBLK*PV,(unsigned)__builtin_amdgcn_readfirstlane(vdst+VS*(slot))); if constexpr(DV128){ glds16(vsrc+64+(long)(t)*KVBLK*PV,(unsigned)__builtin_amdgcn_readfirstlane(vdst+VS*(slot)+8192)); } }while(0)
; template<int THRL,bool DV128,int PQ,int PK,int PV,int PO> __device__ __forceinline__ void attn_unit(const bf16*Qb,const bf16*__restrict__ Kb,const bf16*__restrict__ Vb,bf16*Ob,const int NT,char*shm,const int wave0){
;   int tid_o=wave0*64+lane_id_v(); asm volatile("":"+v"(tid_o)); const int tid=tid_o,lane=tid&63,r32=lane&31,hi=lane>>5; const int wid=__builtin_amdgcn_readfirstlane(tid>>6);
;   const bf16*Qw=Qb+(long)(wid*QBLK)*PQ;
;   const bf16*Kh=Kb,*Vh=Vb;
;   const unsigned lds0=(unsigned)(uintptr_t)shm;
;   constexpr int VS=DV128?2:1, L_WS=LDS_V+NSLOT*SLOTB*VS, L_OST=L_WS+NW*64*4;
;   float*wsf=(float*)(shm+L_WS)+wid*64;
;   const bf16*ksrc=Kh+(long)lane*PK+wid*8;
;   const bf16*vsrc=Vh+(long)(16*(wid&3)+(lane>>2))*PV+(wid>>2)*32+(lane&3)*8;
;   const unsigned kdst=lds0+LDS_K+wid*1024, vdst=lds0+LDS_V+wid*1024;
;     ...
;   const char*Kbase=shm+LDS_K; bf16x8 kf[8];
;   const lds_cptr shm3=(lds_cptr)shm; const lds_cptr kp0=shm3+LDS_K+hi*1024+r32*16; const lds_cptr vp0=shm3+LDS_V+((lane>>4)&1)*32+(lane&3)*8+(4*hi+((lane&15)>>2))*64;
;   DMA_K(0,0);DMA_V(0,0);DMA_K(1,SLOTB);
;   bf16x8 qr[4];
;   #pragma unroll
;   for(int d0=0;d0<4;++d0)qr[d0]=*reinterpret_cast<const bf16x8*>(&Qw[(long)r32*PQ+d0*16+hi*8]);
;   float mhat=0.f,l_reg=0.f;f32x16 o[4];o[0]=f32x16{};o[1]=f32x16{};o[2]=f32x16{};o[3]=f32x16{};f32x16 negm=f32x16{};asm volatile("":"+v"(negm));
.LBB0_642:
	s_and_b32 s61, s10, 3
	s_mov_b64 s[6:7], s[58:59]
	s_lshl_b32 s5, s61, 7
	s_add_u32 s12, s6, s5
	s_addc_u32 s13, s7, 0
	s_ashr_i32 s5, s4, 31
	s_lshl_b64 s[6:7], s[4:5], 9
	s_add_u32 s35, s12, s6
	s_addc_u32 s44, s13, s7
	s_lshl_b32 s65, s11, 1
	s_bfe_u32 s66, s10, 0x10001
	s_or_b32 s5, s65, s66
	s_mov_b64 s[12:13], s[58:59]
	s_mul_hi_i32 s6, s5, 0x108000
	s_mul_i32 s5, s5, 0x108000
	s_add_u32 s36, s12, s5
	s_mov_b64 s[14:15], s[58:59]
	s_mov_b64 s[10:11], s[58:59]
	s_addc_u32 s37, s13, s6
	v_mbcnt_lo_u32_b32 v0, -1, 0
	v_mbcnt_hi_u32_b32 v0, -1, v0
	s_add_u32 s40, s14, s5
	v_add_u32_e32 v84, s89, v0
	s_addc_u32 s41, s15, s6
	v_readfirstlane_b32 s67, v84
	s_ashr_i32 s5, s67, 6
	s_lshl_b32 s6, s5, 5
	s_ashr_i32 s7, s6, 31
	s_lshl_b64 s[42:43], s[6:7], 9
	s_add_u32 s42, s35, s42
	s_addc_u32 s43, s44, s43
	s_lshl_b32 s35, s5, 4
	v_bfe_u32 v190, v84, 2, 4
	v_and_b32_e32 v196, 63, v84
	v_and_or_b32 v2, s35, 48, v190
	v_lshlrev_b32_e32 v208, 4, v196
	v_lshlrev_b32_e32 v2, 7, v2
	v_mov_b32_e32 v3, v209
	s_ashr_i32 s35, s67, 3
	v_lshl_add_u64 v[0:1], s[36:37], 0, v[208:209]
	s_lshl_b32 s36, s5, 9
	v_lshl_add_u64 v[2:3], s[40:41], 0, v[2:3]
	s_and_b32 s40, s35, 0xffffffe0
	v_lshlrev_b32_e32 v199, 3, v84
	s_ashr_i32 s37, s36, 31
	s_ashr_i32 s41, s40, 31
	v_and_b32_e32 v56, 24, v199
	s_and_b32 s7, s67, 0x3fffffc0
	v_lshl_add_u64 v[80:81], s[36:37], 1, v[0:1]
	s_mov_b64 s[44:45], 0x14900000
	v_lshl_add_u64 v[2:3], s[40:41], 1, v[2:3]
	v_lshlrev_b32_e32 v4, 1, v56
	v_mov_b32_e32 v5, v209
	s_lshl_b32 s35, s5, 10
	v_lshl_add_u64 v[0:1], v[80:81], 0, s[44:45]
	v_lshl_add_u64 v[82:83], v[2:3], 0, v[4:5]
	s_mov_b64 s[44:45], 0x15200000
	s_cmp_lg_u32 0, -1
	v_lshl_add_u64 v[2:3], v[82:83], 0, s[44:45]
	s_cselect_b32 s44, 0, 0
	s_add_i32 s35, s35, s44
	s_mov_b32 s44, m0
	s_mov_b32 m0, s35
	s_nop 0
	global_load_lds_dwordx4 v[0:1], off
	s_mov_b32 m0, s44
	s_add_i32 s49, s35, 0x6000
	s_mov_b32 s44, m0
	s_mov_b32 m0, s49
	s_nop 0
	global_load_lds_dwordx4 v[2:3], off
	s_mov_b32 m0, s44
	s_mov_b64 s[44:45], 0x14902000
	v_and_b32_e32 v197, 31, v84
	v_lshl_add_u64 v[0:1], v[80:81], 0, s[44:45]
	v_bfe_u32 v198, v84, 5, 1
	s_add_i32 s44, s35, 0x2000
	s_mov_b32 s45, m0
	s_mov_b32 m0, s44
	s_nop 0
	global_load_lds_dwordx4 v[0:1], off
	s_mov_b32 m0, s45
	v_lshlrev_b32_e32 v0, 9, v197
	v_lshl_or_b32 v0, v198, 4, v0
	v_mov_b32_e32 v1, v209
	v_lshl_add_u64 v[0:1], s[42:43], 0, v[0:1]
	s_mov_b32 s42, 0x13800000
	v_add_co_u32_e32 v2, vcc, s42, v0
	s_mov_b64 s[42:43], 0x13800000
	s_nop 0
	v_addc_co_u32_e32 v3, vcc, 0, v1, vcc
	flat_load_dwordx4 v[140:143], v[2:3]
	v_lshl_add_u64 v[0:1], v[0:1], 0, s[42:43]
	flat_load_dwordx4 v[132:135], v[0:1] offset:32
	flat_load_dwordx4 v[120:123], v[0:1] offset:64
	flat_load_dwordx4 v[112:115], v[0:1] offset:96
	v_lshlrev_b32_e32 v2, 10, v198
	v_lshlrev_b32_e32 v3, 4, v197
	v_mov_b32_e32 v14, v209
	v_mov_b32_e32 v15, v209
	v_add3_u32 v202, 0, v2, v3
	v_mov_b32_e32 v0, v209
	v_mov_b32_e32 v1, v209
	v_mov_b32_e32 v2, v209
	v_mov_b32_e32 v3, v209
	v_mov_b32_e32 v4, v209
	v_mov_b32_e32 v6, v209
	v_mov_b32_e32 v7, v209
	v_mov_b32_e32 v8, v209
	v_mov_b32_e32 v9, v209
	v_mov_b32_e32 v10, v209
	v_mov_b32_e32 v11, v209
	v_mov_b32_e32 v12, v209
	v_mov_b32_e32 v13, v209
	v_mov_b64_e32 v[30:31], v[14:15]
	v_mov_b64_e32 v[28:29], v[12:13]
	v_mov_b64_e32 v[26:27], v[10:11]
	v_mov_b64_e32 v[24:25], v[8:9]
	v_mov_b64_e32 v[22:23], v[6:7]
	v_mov_b64_e32 v[20:21], v[4:5]
	v_mov_b64_e32 v[18:19], v[2:3]
	v_mov_b64_e32 v[16:17], v[0:1]
	s_mov_b64 s[42:43], 0x14904000
	v_lshl_add_u64 v[32:33], v[80:81], 0, s[42:43]
	s_add_i32 s42, s35, 0x4000
	s_mov_b32 s43, m0
	s_mov_b32 m0, s42
	s_nop 0
	global_load_lds_dwordx4 v[32:33], off
	s_mov_b32 m0, s43
	s_waitcnt vmcnt(3) lgkmcnt(0)
	s_barrier
; __device__ __forceinline__ void qkt(f32x16&p0,f32x16&p1,const char*Kslot,const bf16x8*qr,const f32x16&negm,int r32,int hi){
;   const char*kb=Kslot+hi*1024+r32*16;
;   #pragma unroll
;   for(int d0=0;d0<4;++d0){
;     const bf16x8 b0=*reinterpret_cast<const bf16x8*>(kb+d0*2048);
;     const bf16x8 b1=*reinterpret_cast<const bf16x8*>(kb+d0*2048+512);
;     if(d0==0){p0=__builtin_amdgcn_mfma_f32_32x32x16_bf16(b0,qr[0],negm,0,0,0);p1=__builtin_amdgcn_mfma_f32_32x32x16_bf16(b1,qr[0],negm,0,0,0);}
;     else{p0=__builtin_amdgcn_mfma_f32_32x32x16_bf16(b0,qr[d0],p0,0,0,0);p1=__builtin_amdgcn_mfma_f32_32x32x16_bf16(b1,qr[d0],p1,0,0,0);}}
; }
; __device__ __forceinline__ void kload8(bf16x8*kf,lds_cptr kp){
;   kf[0]=*(const __attribute__((address_space(3))) bf16x8*)(kp);      kf[1]=*(const __attribute__((address_space(3))) bf16x8*)(kp+512);
;   kf[2]=*(const __attribute__((address_space(3))) bf16x8*)(kp+2048); kf[3]=*(const __attribute__((address_space(3))) bf16x8*)(kp+2560);
;   kf[4]=*(const __attribute__((address_space(3))) bf16x8*)(kp+4096); kf[5]=*(const __attribute__((address_space(3))) bf16x8*)(kp+4608);
;   kf[6]=*(const __attribute__((address_space(3))) bf16x8*)(kp+6144); kf[7]=*(const __attribute__((address_space(3))) bf16x8*)(kp+6656);
; }
; __device__ __forceinline__ void kload2(bf16x8*kf,lds_cptr kp,int j){ kf[2*j]=*(const __attribute__((address_space(3))) bf16x8*)(kp+j*2048); kf[2*j+1]=*(const __attribute__((address_space(3))) bf16x8*)(kp+j*2048+512); }
; __device__ __forceinline__ s16x4 vtr(lds_cptr p){ return __builtin_bit_cast(s16x4,__builtin_amdgcn_ds_read_tr16_b64_v4i16((__attribute__((address_space(3))) v4i16_t*)p)); }
; __device__ __forceinline__ float rowmax(const f32x16&p0,const f32x16&p1){
;   float a=max3f(p0[0],p0[1],p1[0]),b=max3f(p0[2],p0[3],p1[1]);a=max3f(a,p1[2],p1[3]);
; template<int THRL,bool DV128,int PQ,int PK,int PV,int PO> __device__ __forceinline__ void attn_unit(const bf16*Qb,const bf16*__restrict__ Kb,const bf16*__restrict__ Vb,bf16*Ob,const int NT,char*shm,const int wave0){
;     ...
;   DMA_K(2,2*SLOTB);
;   WAIT_BAR(3);
;   qkt(pA0,pA1,Kbase,qr,negm,r32,hi);asm volatile("s_nop 15\n\ts_nop 7":"+v"(pA0),"+v"(pA1));CMASK(pA0,pA1,0);
;   START(pA0,pA1);
;   _Pragma("unroll") for(int r=0;r<16;++r)pA1[r]=__builtin_amdgcn_exp2f(pA1[r]);
;   WAIT_BAR(0);
;   DMA_K(3,0);DMA_V(1,SLOTB);
;   ROT();
;   kload8(kf,kp0+sl_cur);
;     ...
;   WB2();
	ds_read_b128 v[48:51], v202
	ds_read_b128 v[52:55], v202 offset:512
	s_waitcnt vmcnt(0) lgkmcnt(0)
	v_mfma_f32_32x32x16_bf16 v[32:47], v[48:51], v[140:143], v[16:31]
	v_lshlrev_b32_e32 v57, 1, v84
	s_lshl_b32 s7, s7, 2
	v_lshlrev_b32_e32 v85, 8, v198
	s_add_i32 s7, s7, 0
	s_mov_b32 s44, 1
	s_mov_b32 s68, 0
	s_movk_i32 s60, 0x2000
	v_mfma_f32_32x32x16_bf16 v[16:31], v[52:55], v[140:143], v[16:31]
	ds_read_b128 v[48:51], v202 offset:2048
	ds_read_b128 v[52:55], v202 offset:2560
	s_movk_i32 s47, 0x4000
	s_andn2_b64 vcc, exec, s[38:39]
	v_cmp_gt_u32_e64 s[38:39], 32, v196
	v_lshlrev_b32_e32 v204, 4, v198
	v_lshl_add_u32 v200, v197, 2, s7
	s_waitcnt lgkmcnt(1)
	v_mfma_f32_32x32x16_bf16 v[32:47], v[48:51], v[132:135], v[32:47]
	s_waitcnt lgkmcnt(0)
	v_mfma_f32_32x32x16_bf16 v[16:31], v[52:55], v[132:135], v[16:31]
	ds_read_b128 v[48:51], v202 offset:4096
	ds_read_b128 v[52:55], v202 offset:4608
	s_waitcnt lgkmcnt(1)
	v_mfma_f32_32x32x16_bf16 v[32:47], v[48:51], v[120:123], v[32:47]
	ds_read_b128 v[48:51], v202 offset:6144
	s_waitcnt lgkmcnt(1)
	v_mfma_f32_32x32x16_bf16 v[16:31], v[52:55], v[120:123], v[16:31]
	ds_read_b128 v[52:55], v202 offset:6656
	s_waitcnt lgkmcnt(1)
	v_mfma_f32_32x32x16_bf16 v[32:47], v[48:51], v[112:115], v[32:47]
	v_lshlrev_b32_e32 v48, 4, v84
	v_and_b32_e32 v49, 32, v57
	v_and_b32_e32 v87, 0xc0, v48
	v_add3_u32 v86, 0, v49, v56
	v_add3_u32 v203, v86, v85, v87
	s_waitcnt lgkmcnt(0)
	v_mfma_f32_32x32x16_bf16 v[16:31], v[52:55], v[112:115], v[16:31]
	s_nop 15
	s_nop 7
	s_nop 0
	v_max3_f32 v48, v32, v33, v16
	v_max3_f32 v49, v34, v35, v17
	s_nop 0
	v_max3_f32 v48, v48, v18, v19
	v_max3_f32 v49, v49, v38, v39
	s_nop 0
	v_max3_f32 v48, v48, v36, v37
	v_max3_f32 v49, v49, v22, v23
	s_nop 0
	v_max3_f32 v48, v48, v20, v21
	v_max3_f32 v49, v49, v42, v43
	s_nop 0
	v_max3_f32 v48, v48, v40, v41
	v_max3_f32 v49, v49, v26, v27
	s_nop 0
	v_max3_f32 v48, v48, v24, v25
	v_max3_f32 v49, v49, v46, v47
	s_nop 0
	v_max3_f32 v48, v48, v44, v45
	v_max3_f32 v49, v49, v30, v31
	s_nop 0
	v_max3_f32 v48, v48, v28, v29
	s_nop 0
	v_max_f32_e32 v48, v48, v49
	s_nop 0
	v_mov_b32_e32 v49, v48
	s_nop 1
	v_permlane32_swap_b32_e32 v48, v49
	v_max_f32_e32 v48, v48, v49
	s_nop 0
	v_add_f32_e32 v201, v209, v48
	v_sub_f32_e32 v49, v32, v48
	v_sub_f32_e32 v50, v33, v48
	v_sub_f32_e32 v51, v34, v48
	v_sub_f32_e32 v52, v35, v48
	v_sub_f32_e32 v53, v36, v48
	s_nop 0
	v_xor_b32_e32 v32, 0x80000000, v201
	v_sub_f32_e32 v54, v37, v48
	v_sub_f32_e32 v55, v38, v48
	v_sub_f32_e32 v56, v39, v48
	v_sub_f32_e32 v57, v40, v48
	v_sub_f32_e32 v58, v41, v48
	v_sub_f32_e32 v59, v42, v48
	v_sub_f32_e32 v60, v43, v48
	v_sub_f32_e32 v61, v44, v48
	v_sub_f32_e32 v62, v45, v48
	v_sub_f32_e32 v63, v46, v48
	v_sub_f32_e32 v79, v47, v48
	v_mov_b32_e32 v33, v32
	v_mov_b32_e32 v34, v32
	v_mov_b32_e32 v35, v32
	v_mov_b32_e32 v36, v32
	v_mov_b32_e32 v37, v32
	v_mov_b32_e32 v38, v32
	v_mov_b32_e32 v39, v32
	v_mov_b32_e32 v40, v32
	v_mov_b32_e32 v41, v32
	v_mov_b32_e32 v42, v32
	v_mov_b32_e32 v43, v32
	v_mov_b32_e32 v44, v32
	v_mov_b32_e32 v45, v32
	v_mov_b32_e32 v46, v32
	v_mov_b32_e32 v47, v32
	v_sub_f32_e32 v16, v16, v48
	v_sub_f32_e32 v17, v17, v48
	s_waitcnt vmcnt(0) lgkmcnt(0)
	s_barrier
	v_sub_f32_e32 v18, v18, v48
	v_sub_f32_e32 v19, v19, v48
	v_sub_f32_e32 v20, v20, v48
	v_sub_f32_e32 v21, v21, v48
	v_sub_f32_e32 v22, v22, v48
	v_sub_f32_e32 v23, v23, v48
	v_sub_f32_e32 v24, v24, v48
	v_sub_f32_e32 v25, v25, v48
	v_sub_f32_e32 v26, v26, v48
	v_sub_f32_e32 v27, v27, v48
	v_sub_f32_e32 v28, v28, v48
	v_sub_f32_e32 v29, v29, v48
	v_sub_f32_e32 v30, v30, v48
	v_sub_f32_e32 v31, v31, v48
	v_exp_f32_e32 v64, v49
	v_exp_f32_e32 v48, v16
	v_exp_f32_e32 v49, v17
	v_lshl_add_u64 v[16:17], v[80:81], 0, s[74:75]
	s_mov_b32 s42, m0
	s_mov_b32 m0, s35
	s_nop 0
	global_load_lds_dwordx4 v[16:17], off
	s_mov_b32 m0, s42
	v_lshl_add_u64 v[16:17], v[82:83], 0, s[84:85]
	s_add_i32 s42, s35, 0x8000
	s_mov_b32 s43, m0
	s_mov_b32 m0, s42
	s_nop 0
	global_load_lds_dwordx4 v[16:17], off
	s_mov_b32 m0, s43
	ds_read_b128 v[172:175], v202 offset:8192
	ds_read_b128 v[168:171], v202 offset:8704
	ds_read_b128 v[164:167], v202 offset:10240
	ds_read_b128 v[160:163], v202 offset:10752
	ds_read_b128 v[156:159], v202 offset:12288
	ds_read_b128 v[152:155], v202 offset:12800
	ds_read_b128 v[148:151], v202 offset:14336
	ds_read_b128 v[144:147], v202 offset:14848
	v_exp_f32_e32 v65, v50
	v_exp_f32_e32 v66, v51
	v_exp_f32_e32 v67, v52
	v_exp_f32_e32 v68, v53
	v_exp_f32_e32 v69, v54
	v_exp_f32_e32 v70, v55
	v_exp_f32_e32 v71, v56
	v_exp_f32_e32 v72, v57
	v_exp_f32_e32 v73, v58
	v_exp_f32_e32 v74, v59
	v_exp_f32_e32 v75, v60
	v_exp_f32_e32 v76, v61
	v_exp_f32_e32 v77, v62
	v_exp_f32_e32 v78, v63
	v_exp_f32_e32 v79, v79
	v_exp_f32_e32 v50, v18
	v_exp_f32_e32 v51, v19
	v_exp_f32_e32 v52, v20
	v_exp_f32_e32 v53, v21
	v_exp_f32_e32 v54, v22
	v_exp_f32_e32 v55, v23
	v_exp_f32_e32 v56, v24
	v_exp_f32_e32 v57, v25
	v_exp_f32_e32 v58, v26
	v_exp_f32_e32 v59, v27
	v_exp_f32_e32 v60, v28
	v_exp_f32_e32 v61, v29
	v_exp_f32_e32 v62, v30
	v_exp_f32_e32 v63, v31
	s_waitcnt vmcnt(2) lgkmcnt(0)
	s_barrier
	v_and_b32_e32 v16, 3, v84
	v_lshlrev_b32_e32 v180, 4, v16
	s_cbranch_vccnz .LBB0_658
	s_lshl_b32 s44, s67, 5
	v_mov_b32_e32 v181, v209
	s_and_b32 s44, s44, 0x1800
	s_add_i32 s42, s66, s65
	v_lshl_add_u64 v[0:1], s[40:41], 1, v[180:181]
	v_lshl_or_b32 v2, v190, 7, s44
	v_mov_b32_e32 v3, v209
	s_lshl_b64 s[44:45], s[36:37], 1
	v_lshl_add_u64 v[0:1], v[0:1], 0, v[2:3]
	s_add_u32 s44, s12, s44
	v_mov_b32_e32 v16, v209
	v_mov_b32_e32 v17, v209
	v_lshl_add_u64 v[182:183], s[14:15], 0, v[0:1]
	s_addc_u32 s45, s13, s45
	v_mov_b32_e32 v18, v209
	v_mov_b32_e32 v19, v209
	v_mov_b32_e32 v20, v209
	v_mov_b32_e32 v21, v209
	v_mov_b32_e32 v22, v209
	v_mov_b32_e32 v23, v209
	v_mov_b32_e32 v24, v209
	v_mov_b32_e32 v25, v209
	v_mov_b32_e32 v26, v209
	v_mov_b32_e32 v27, v209
	v_mov_b32_e32 v28, v209
	v_mov_b32_e32 v29, v209
	v_mov_b32_e32 v30, v209
	v_mov_b32_e32 v31, v209
	v_mov_b64_e32 v[0:1], v[16:17]
	s_mul_hi_i32 s43, s42, 0x108000
	s_mul_i32 s42, s42, 0x108000
	v_lshl_add_u64 v[184:185], s[44:45], 0, v[208:209]
	s_mov_b32 s44, 0
	s_movk_i32 s68, 0x4000
	s_movk_i32 s70, 0x2000
	v_mov_b32_e32 v192, 0
	s_mov_b32 s69, 6
	v_mov_b64_e32 v[2:3], v[18:19]
	v_mov_b64_e32 v[4:5], v[20:21]
	v_mov_b64_e32 v[6:7], v[22:23]
	v_mov_b64_e32 v[8:9], v[24:25]
	v_mov_b64_e32 v[10:11], v[26:27]
	v_mov_b64_e32 v[12:13], v[28:29]
	v_mov_b64_e32 v[14:15], v[30:31]

; __device__ __forceinline__ int lane_id_v() { int l; asm volatile("v_mbcnt_lo_u32_b32 %0, -1, 0\n\tv_mbcnt_hi_u32_b32 %0, -1, %0" : "=v"(l)); return l; }
;   #define DMA_K(t,slot) glds16(ksrc+(long)(t)*KVBLK*PK,(unsigned)__builtin_amdgcn_readfirstlane(kdst+(slot)))
;   #define DMA_V(t,slot) do{ glds16(vsrc+(long)(t)*KVBLK*PV,(unsigned)__builtin_amdgcn_readfirstlane(vdst+VS*(slot))); if constexpr(DV128){ glds16(vsrc+64+(long)(t)*KVBLK*PV,(unsigned)__builtin_amdgcn_readfirstlane(vdst+VS*(slot)+8192)); } }while(0)
; template<int THRL,bool DV128,int PQ,int PK,int PV,int PO> __device__ __forceinline__ void attn_unit(const bf16*Qb,const bf16*__restrict__ Kb,const bf16*__restrict__ Vb,bf16*Ob,const int NT,char*shm,const int wave0){
;   int tid_o=wave0*64+lane_id_v(); asm volatile("":"+v"(tid_o)); const int tid=tid_o,lane=tid&63,r32=lane&31,hi=lane>>5; const int wid=__builtin_amdgcn_readfirstlane(tid>>6);
;   const bf16*Qw=Qb+(long)(wid*QBLK)*PQ;
;   const bf16*Kh=Kb,*Vh=Vb;
;   const unsigned lds0=(unsigned)(uintptr_t)shm;
;   constexpr int VS=DV128?2:1, L_WS=LDS_V+NSLOT*SLOTB*VS, L_OST=L_WS+NW*64*4;
;   float*wsf=(float*)(shm+L_WS)+wid*64;
;   const bf16*ksrc=Kh+(long)lane*PK+wid*8;
;   const bf16*vsrc=Vh+(long)(16*(wid&3)+(lane>>2))*PV+(wid>>2)*32+(lane&3)*8;
;   const unsigned kdst=lds0+LDS_K+wid*1024, vdst=lds0+LDS_V+wid*1024;
;     ...
;   const char*Kbase=shm+LDS_K; bf16x8 kf[8];
;   const lds_cptr shm3=(lds_cptr)shm; const lds_cptr kp0=shm3+LDS_K+hi*1024+r32*16; const lds_cptr vp0=shm3+LDS_V+((lane>>4)&1)*32+(lane&3)*8+(4*hi+((lane&15)>>2))*64;
;   DMA_K(0,0);DMA_V(0,0);DMA_K(1,SLOTB);
;   bf16x8 qr[4];
;   #pragma unroll
;   for(int d0=0;d0<4;++d0)qr[d0]=*reinterpret_cast<const bf16x8*>(&Qw[(long)r32*PQ+d0*16+hi*8]);
;   float mhat=0.f,l_reg=0.f;f32x16 o[4];o[0]=f32x16{};o[1]=f32x16{};o[2]=f32x16{};o[3]=f32x16{};f32x16 negm=f32x16{};asm volatile("":"+v"(negm));
.LBB0_719:
	s_bfe_u32 s35, s11, 0x20001
	s_lshl_b32 s5, s11, 7
	s_and_b32 s46, s11, 1
	s_mov_b64 s[6:7], s[58:59]
	s_lshl_b32 s66, s35, 1
	s_and_b32 s5, s5, 0x380
	s_add_u32 s12, s6, s5
	s_addc_u32 s13, s7, 0
	s_ashr_i32 s5, s4, 31
	s_lshl_b64 s[6:7], s[4:5], 10
	s_add_u32 s44, s12, s6
	s_addc_u32 s45, s13, s7
	s_and_b32 s67, s11, -8
	s_or_b32 s5, s66, s67
	s_or_b32 s5, s5, s46
	s_mov_b64 s[12:13], s[58:59]
	s_mul_hi_i32 s6, s5, 0x108000
	s_mul_i32 s5, s5, 0x108000
	s_add_u32 s36, s12, s5
	s_addc_u32 s37, s13, s6
	s_lshl_b32 s68, s10, 2
	s_mov_b64 s[14:15], s[58:59]
	s_or_b32 s5, s68, s35
	s_mov_b64 s[10:11], s[58:59]
	s_mul_hi_i32 s6, s5, 0x210000
	s_mul_i32 s5, s5, 0x210000
	v_mbcnt_lo_u32_b32 v0, -1, 0
	v_mbcnt_hi_u32_b32 v0, -1, v0
	s_add_u32 s40, s14, s5
	v_add_u32_e32 v60, s89, v0
	s_addc_u32 s41, s15, s6
	v_readfirstlane_b32 s69, v60
	s_ashr_i32 s5, s69, 6
	s_lshl_b32 s6, s5, 5
	s_ashr_i32 s7, s6, 31
	v_and_b32_e32 v243, 63, v60
	s_lshl_b64 s[42:43], s[6:7], 10
	s_add_u32 s42, s44, s42
	v_lshlrev_b32_e32 v208, 4, v243
	s_addc_u32 s43, s45, s43
	v_lshl_add_u64 v[0:1], s[36:37], 0, v[208:209]
	s_lshl_b32 s36, s5, 9
	s_ashr_i32 s37, s36, 31
	v_lshl_add_u64 v[48:49], s[36:37], 1, v[0:1]
	s_mov_b64 s[44:45], 0x17c00000
	v_lshl_add_u64 v[0:1], v[48:49], 0, s[44:45]
	s_lshl_b32 s44, s5, 4
	v_bfe_u32 v216, v60, 2, 4
	v_and_or_b32 v2, s44, 48, v216
	v_lshlrev_b32_e32 v2, 8, v2
	v_mov_b32_e32 v3, v209
	v_lshl_add_u64 v[2:3], s[40:41], 0, v[2:3]
	s_ashr_i32 s40, s69, 3
	s_andn2_b32 s40, s40, 31
	v_lshlrev_b32_e32 v246, 3, v60
	s_ashr_i32 s41, s40, 31
	v_and_b32_e32 v61, 24, v246
	s_and_b32 s7, s69, 0x3fffffc0
	v_lshl_add_u64 v[2:3], s[40:41], 1, v[2:3]
	v_lshlrev_b32_e32 v4, 1, v61
	v_mov_b32_e32 v5, v209
	s_lshl_b32 s49, s5, 10
	v_lshl_add_u64 v[50:51], v[2:3], 0, v[4:5]
	s_mov_b64 s[44:45], 0x19d00000
	s_cmp_lg_u32 0, -1
	v_lshl_add_u64 v[2:3], v[50:51], 0, s[44:45]
	s_cselect_b32 s44, 0, 0
	s_add_i32 s49, s49, s44
	s_mov_b32 s44, m0
	s_mov_b32 m0, s49
	s_nop 0
	global_load_lds_dwordx4 v[0:1], off
	s_mov_b32 m0, s44
	s_add_i32 s60, s49, 0x6000
	s_mov_b32 s44, m0
	s_mov_b32 m0, s60
	s_nop 0
	global_load_lds_dwordx4 v[2:3], off
	s_mov_b32 m0, s44
	s_mov_b64 s[44:45], 0x19d00080
	v_lshl_add_u64 v[0:1], v[50:51], 0, s[44:45]
	s_add_i32 s44, s49, 0x8000
	s_mov_b32 s45, m0
	s_mov_b32 m0, s44
	s_nop 0
	global_load_lds_dwordx4 v[0:1], off
	s_mov_b32 m0, s45
	s_mov_b64 s[44:45], 0x17c02000
	v_and_b32_e32 v244, 31, v60
	v_lshl_add_u64 v[0:1], v[48:49], 0, s[44:45]
	v_bfe_u32 v245, v60, 5, 1
	s_add_i32 s44, s49, 0x2000
	s_mov_b32 s45, m0
	s_mov_b32 m0, s44
	s_nop 0
	global_load_lds_dwordx4 v[0:1], off
	s_mov_b32 m0, s45
	v_lshlrev_b32_e32 v0, 10, v244
	v_lshl_or_b32 v0, v245, 4, v0
	v_mov_b32_e32 v1, v209
	v_lshl_add_u64 v[0:1], s[42:43], 0, v[0:1]
	s_mov_b32 s42, 0x15b00000
	v_add_co_u32_e32 v2, vcc, s42, v0
	s_mov_b64 s[42:43], 0x15b00000
	s_nop 0
	v_addc_co_u32_e32 v3, vcc, 0, v1, vcc
	flat_load_dwordx4 v[172:175], v[2:3]
	v_lshl_add_u64 v[0:1], v[0:1], 0, s[42:43]
	flat_load_dwordx4 v[168:171], v[0:1] offset:32
	flat_load_dwordx4 v[164:167], v[0:1] offset:64
	flat_load_dwordx4 v[156:159], v[0:1] offset:96
	v_lshlrev_b32_e32 v2, 10, v245
	v_lshlrev_b32_e32 v3, 4, v244
	v_mov_b32_e32 v14, v209
	v_mov_b32_e32 v15, v209
	v_add3_u32 v250, 0, v2, v3
	v_mov_b32_e32 v0, v209
	v_mov_b32_e32 v1, v209
	v_mov_b32_e32 v2, v209
	v_mov_b32_e32 v3, v209
	v_mov_b32_e32 v4, v209
	v_mov_b32_e32 v6, v209
	v_mov_b32_e32 v7, v209
	v_mov_b32_e32 v8, v209
	v_mov_b32_e32 v9, v209
	v_mov_b32_e32 v10, v209
	v_mov_b32_e32 v11, v209
	v_mov_b32_e32 v12, v209
	v_mov_b32_e32 v13, v209
	v_mov_b64_e32 v[30:31], v[14:15]
	v_mov_b64_e32 v[28:29], v[12:13]
	v_mov_b64_e32 v[26:27], v[10:11]
	v_mov_b64_e32 v[24:25], v[8:9]
	v_mov_b64_e32 v[22:23], v[6:7]
	v_mov_b64_e32 v[20:21], v[4:5]
	v_mov_b64_e32 v[18:19], v[2:3]
	v_mov_b64_e32 v[16:17], v[0:1]
	s_mov_b64 s[42:43], 0x17c04000
	v_lshl_add_u64 v[32:33], v[48:49], 0, s[42:43]
	s_add_i32 s42, s49, 0x4000
	s_mov_b32 s43, m0
	s_mov_b32 m0, s42
	s_nop 0
	global_load_lds_dwordx4 v[32:33], off
	s_mov_b32 m0, s43
	s_waitcnt vmcnt(3) lgkmcnt(0)
	s_barrier
	ds_read_b128 v[52:55], v250
	ds_read_b128 v[56:59], v250 offset:512
	s_waitcnt vmcnt(0) lgkmcnt(0)
	v_mfma_f32_32x32x16_bf16 v[32:47], v[52:55], v[172:175], v[16:31]
	s_mov_b64 s[70:71], 0x17c06000
	v_lshlrev_b32_e32 v62, 1, v60
	s_lshl_b32 s7, s7, 2
	s_add_i32 s7, s7, 0
	s_add_i32 s7, s7, 0x12000
	s_mov_b32 s42, 1
	s_mov_b32 s61, 0
	v_mfma_f32_32x32x16_bf16 v[16:31], v[56:59], v[172:175], v[16:31]
	ds_read_b128 v[52:55], v250 offset:2048
	ds_read_b128 v[56:59], v250 offset:2560
	s_movk_i32 s65, 0x2000
	s_movk_i32 s44, 0x4000
	s_andn2_b64 vcc, exec, s[38:39]
	v_cmp_gt_u32_e64 s[38:39], 32, v243
	v_lshlrev_b32_e32 v251, 4, v245
	v_lshl_add_u32 v247, v244, 2, s7
	s_waitcnt lgkmcnt(1)
	v_mfma_f32_32x32x16_bf16 v[32:47], v[52:55], v[168:171], v[32:47]
	s_waitcnt lgkmcnt(0)
	v_mfma_f32_32x32x16_bf16 v[16:31], v[56:59], v[168:171], v[16:31]
	ds_read_b128 v[52:55], v250 offset:4096
	ds_read_b128 v[56:59], v250 offset:4608
	s_waitcnt lgkmcnt(1)
	v_mfma_f32_32x32x16_bf16 v[32:47], v[52:55], v[164:167], v[32:47]
	s_waitcnt lgkmcnt(0)
	v_mfma_f32_32x32x16_bf16 v[16:31], v[56:59], v[164:167], v[16:31]
	ds_read_b128 v[52:55], v250 offset:6144
	ds_read_b128 v[56:59], v250 offset:6656
	s_waitcnt lgkmcnt(1)
	v_mfma_f32_32x32x16_bf16 v[32:47], v[52:55], v[156:159], v[32:47]
	v_and_b32_e32 v52, 32, v62
	v_lshlrev_b32_e32 v54, 4, v60
	v_add3_u32 v52, 0, v52, v61
	v_lshlrev_b32_e32 v53, 8, v245
	v_and_b32_e32 v54, 0xc0, v54
	v_add3_u32 v248, v52, v53, v54
	s_waitcnt lgkmcnt(0)
	v_mfma_f32_32x32x16_bf16 v[16:31], v[56:59], v[156:159], v[16:31]
	s_nop 15
	s_nop 7
	s_nop 0
	v_max3_f32 v55, v32, v33, v16
	v_max3_f32 v56, v34, v35, v17
	s_nop 0
	v_max3_f32 v55, v55, v18, v19
	v_max3_f32 v56, v56, v38, v39
	s_nop 0
	v_max3_f32 v55, v55, v36, v37
	v_max3_f32 v56, v56, v22, v23
	s_nop 0
	v_max3_f32 v55, v55, v20, v21
	v_max3_f32 v56, v56, v42, v43
	s_nop 0
	v_max3_f32 v55, v55, v40, v41
	v_max3_f32 v56, v56, v26, v27
	s_nop 0
	v_max3_f32 v55, v55, v24, v25
	v_max3_f32 v56, v56, v46, v47
	s_nop 0
	v_max3_f32 v55, v55, v44, v45
	v_max3_f32 v56, v56, v30, v31
	s_nop 0
	v_max3_f32 v55, v55, v28, v29
	s_nop 0
	v_max_f32_e32 v55, v55, v56
	s_nop 0
	v_mov_b32_e32 v56, v55
	s_nop 1
	v_permlane32_swap_b32_e32 v55, v56
	v_max_f32_e32 v55, v55, v56
	s_nop 0
	v_add_f32_e32 v249, v209, v55
	v_sub_f32_e32 v16, v16, v55
	v_sub_f32_e32 v17, v17, v55
	v_sub_f32_e32 v32, v32, v55
	v_sub_f32_e32 v33, v33, v55
	v_sub_f32_e32 v34, v34, v55
	s_nop 0
	v_xor_b32_e32 v64, 0x80000000, v249
	v_mov_b32_e32 v65, v64
	v_mov_b32_e32 v66, v64
	v_mov_b32_e32 v67, v64
	v_mov_b32_e32 v68, v64
	v_mov_b32_e32 v69, v64
	v_mov_b32_e32 v70, v64
	v_mov_b32_e32 v71, v64
	v_mov_b32_e32 v72, v64
	v_mov_b32_e32 v73, v64
	v_mov_b32_e32 v74, v64
	v_mov_b32_e32 v75, v64
	v_mov_b32_e32 v76, v64
	v_mov_b32_e32 v77, v64
	v_mov_b32_e32 v78, v64
	v_mov_b32_e32 v79, v64
	s_waitcnt vmcnt(0) lgkmcnt(0)
	s_barrier
; #define WAIT_BAR(N) asm volatile("s_waitcnt vmcnt(" #N ") lgkmcnt(0)\n\ts_barrier":::"memory")
;   #define DMA_K(t,slot) glds16(ksrc+(long)(t)*KVBLK*PK,(unsigned)__builtin_amdgcn_readfirstlane(kdst+(slot)))
;   #define DMA_V(t,slot) do{ glds16(vsrc+(long)(t)*KVBLK*PV,(unsigned)__builtin_amdgcn_readfirstlane(vdst+VS*(slot))); if constexpr(DV128){ glds16(vsrc+64+(long)(t)*KVBLK*PV,(unsigned)__builtin_amdgcn_readfirstlane(vdst+VS*(slot)+8192)); } }while(0)
;   #define CMASK(P0,P1,t) do{}while(0)
;   #define START(P0,P1) do{ const float rm=rowmax(P0,P1); resc=false; \
;     { const float dl=rm; mhat=fadd_s(mhat,dl); \
;       _Pragma("unroll") for(int r=0;r<16;++r){P0[r]=fsub_s(P0[r],dl);P1[r]=fsub_s(P1[r],dl);} \
;       _Pragma("unroll") for(int r=0;r<16;++r)negm[r]=-mhat; asm volatile("":"+v"(negm)); } \
;     _Pragma("unroll") for(int r=0;r<16;++r)P0[r]=__builtin_amdgcn_exp2f(P0[r]); }while(0)
;   #define ROT() do{sl_prev=sl_cur;sl_cur=sl_next;sl_next=(sl_next==(NSLOT-1)*SLOTB)?0:sl_next+SLOTB;}while(0)
;   #define WB2() do{ if constexpr(DV128){WAIT_BAR(3);}else{WAIT_BAR(2);} }while(0)
;   #define CMASK(P0,P1,t) do{}while(0)
;   #define CMASK(P0,P1,t) do{}while(0)
; template<int THRL,bool DV128,int PQ,int PK,int PV,int PO> __device__ __forceinline__ void attn_unit(const bf16*Qb,const bf16*__restrict__ Kb,const bf16*__restrict__ Vb,bf16*Ob,const int NT,char*shm,const int wave0){
;     ...
;   qkt(pA0,pA1,Kbase,qr,negm,r32,hi);asm volatile("s_nop 15\n\ts_nop 7":"+v"(pA0),"+v"(pA1));CMASK(pA0,pA1,0);
;   START(pA0,pA1);
;   _Pragma("unroll") for(int r=0;r<16;++r)pA1[r]=__builtin_amdgcn_exp2f(pA1[r]);
;   WAIT_BAR(0);
;   DMA_K(3,0);DMA_V(1,SLOTB);
;   ROT();
;   kload8(kf,kp0+sl_cur);
;     ...
;   WB2();
;   s16x4 vlo[8],vhi[8]; u32x4 pw0,pw1,pw2,pw3;
	v_exp_f32_e32 v80, v16
	v_exp_f32_e32 v81, v17
	v_lshl_add_u64 v[16:17], v[48:49], 0, s[70:71]
	s_mov_b32 s43, m0
	s_mov_b32 m0, s49
	s_nop 0
	global_load_lds_dwordx4 v[16:17], off
	s_mov_b32 m0, s43
	s_mov_b64 s[70:71], 0x19d04000
	v_lshl_add_u64 v[16:17], v[50:51], 0, s[70:71]
	s_add_i32 s43, s49, 0xa000
	s_mov_b32 s45, m0
	s_mov_b32 m0, s43
	s_nop 0
	global_load_lds_dwordx4 v[16:17], off
	s_mov_b32 m0, s45
	s_mov_b64 s[70:71], 0x19d04080
	v_lshl_add_u64 v[16:17], v[50:51], 0, s[70:71]
	s_add_i32 s43, s49, 0xc000
	s_mov_b32 s45, m0
	s_mov_b32 m0, s43
	s_nop 0
	global_load_lds_dwordx4 v[16:17], off
	s_mov_b32 m0, s45
	ds_read_b128 v[204:207], v250 offset:8192
	ds_read_b128 v[200:203], v250 offset:8704
	ds_read_b128 v[196:199], v250 offset:10240
	ds_read_b128 v[192:195], v250 offset:10752
	ds_read_b128 v[188:191], v250 offset:12288
	ds_read_b128 v[184:187], v250 offset:12800
	ds_read_b128 v[180:183], v250 offset:14336
	ds_read_b128 v[176:179], v250 offset:14848
	v_sub_f32_e32 v18, v18, v55
	v_sub_f32_e32 v35, v35, v55
	v_sub_f32_e32 v19, v19, v55
	v_sub_f32_e32 v36, v36, v55
	v_sub_f32_e32 v20, v20, v55
	v_sub_f32_e32 v37, v37, v55
	v_sub_f32_e32 v21, v21, v55
	v_sub_f32_e32 v38, v38, v55
	v_sub_f32_e32 v22, v22, v55
	v_sub_f32_e32 v39, v39, v55
	v_sub_f32_e32 v23, v23, v55
	v_sub_f32_e32 v40, v40, v55
	v_sub_f32_e32 v24, v24, v55
	v_sub_f32_e32 v41, v41, v55
	v_sub_f32_e32 v25, v25, v55
	v_sub_f32_e32 v42, v42, v55
	v_sub_f32_e32 v26, v26, v55
	v_sub_f32_e32 v43, v43, v55
	v_sub_f32_e32 v27, v27, v55
	v_sub_f32_e32 v44, v44, v55
	v_sub_f32_e32 v28, v28, v55
	v_sub_f32_e32 v45, v45, v55
	v_sub_f32_e32 v29, v29, v55
	v_sub_f32_e32 v46, v46, v55
	v_sub_f32_e32 v30, v30, v55
	v_sub_f32_e32 v47, v47, v55
	v_sub_f32_e32 v31, v31, v55
	v_exp_f32_e32 v96, v32
	v_exp_f32_e32 v97, v33
	v_exp_f32_e32 v98, v34
	v_exp_f32_e32 v99, v35
	v_exp_f32_e32 v100, v36
	v_exp_f32_e32 v101, v37
	v_exp_f32_e32 v102, v38
	v_exp_f32_e32 v103, v39
	v_exp_f32_e32 v104, v40
	v_exp_f32_e32 v105, v41
	v_exp_f32_e32 v106, v42
	v_exp_f32_e32 v107, v43
	v_exp_f32_e32 v108, v44
	v_exp_f32_e32 v109, v45
	v_exp_f32_e32 v110, v46
	v_exp_f32_e32 v111, v47
	v_exp_f32_e32 v82, v18
	v_exp_f32_e32 v83, v19
	v_exp_f32_e32 v84, v20
	v_exp_f32_e32 v85, v21
	v_exp_f32_e32 v86, v22
	v_exp_f32_e32 v87, v23
	v_exp_f32_e32 v88, v24
	v_exp_f32_e32 v89, v25
	v_exp_f32_e32 v90, v26
	v_exp_f32_e32 v91, v27
	v_exp_f32_e32 v92, v28
	v_exp_f32_e32 v93, v29
	v_exp_f32_e32 v94, v30
	v_exp_f32_e32 v95, v31
	s_waitcnt vmcnt(3) lgkmcnt(0)
	s_barrier
	v_and_b32_e32 v16, 3, v60
	v_lshlrev_b32_e32 v210, 4, v16
	s_cbranch_vccnz .LBB0_735
	s_add_i32 s42, s68, s35
	s_mul_hi_i32 s44, s42, 0x210000
	s_mul_i32 s45, s42, 0x210000
	s_lshl_b64 s[42:43], s[40:41], 1
	s_add_u32 s42, s42, s45
	v_mov_b32_e32 v211, v209
	s_addc_u32 s43, s43, s44
	v_lshl_add_u64 v[0:1], s[42:43], 0, v[210:211]
	s_lshl_b32 s42, s69, 6
	s_and_b32 s42, s42, 0x3000
	v_lshl_or_b32 v2, v216, 8, s42
	v_mov_b32_e32 v3, v209
	v_lshl_add_u64 v[0:1], v[0:1], 0, v[2:3]
	v_lshl_add_u64 v[0:1], s[14:15], 0, v[0:1]
	s_mov_b64 s[42:43], 0x19d0c080
	v_lshl_add_u64 v[212:213], v[0:1], 0, s[42:43]
	s_add_i32 s42, s67, s66
	s_add_i32 s42, s42, s46
	s_mul_hi_i32 s44, s42, 0x108000
	s_mul_i32 s45, s42, 0x108000
	s_lshl_b64 s[42:43], s[36:37], 1
	s_add_u32 s42, s12, s42
	s_addc_u32 s43, s13, s43
	s_add_u32 s42, s42, s45
	s_addc_u32 s43, s43, s44
	v_lshl_add_u64 v[0:1], s[42:43], 0, v[208:209]
	s_mov_b64 s[42:43], 0x17c0a000
	v_mov_b32_e32 v32, v209
	v_mov_b32_e32 v33, v209
	v_mov_b32_e32 v46, v209
	v_mov_b32_e32 v47, v209
	v_lshl_add_u64 v[214:215], v[0:1], 0, s[42:43]
	v_mov_b32_e32 v34, v209
	v_mov_b32_e32 v35, v209
	v_mov_b32_e32 v36, v209
	v_mov_b32_e32 v37, v209
	v_mov_b32_e32 v38, v209
	v_mov_b32_e32 v39, v209
	v_mov_b32_e32 v40, v209
	v_mov_b32_e32 v41, v209
	v_mov_b32_e32 v42, v209
	v_mov_b32_e32 v43, v209
	v_mov_b32_e32 v44, v209
	v_mov_b32_e32 v45, v209
	v_mov_b64_e32 v[62:63], v[46:47]
	v_mov_b64_e32 v[16:17], v[32:33]
	v_mov_b64_e32 v[0:1], v[32:33]
	s_mov_b32 s70, 6
	s_mov_b32 s72, 0
	s_movk_i32 s61, 0x4000
	s_movk_i32 s71, 0x2000
	v_mov_b32_e32 v252, 0
	v_mov_b64_e32 v[60:61], v[44:45]
	v_mov_b64_e32 v[58:59], v[42:43]
	v_mov_b64_e32 v[56:57], v[40:41]
	v_mov_b64_e32 v[54:55], v[38:39]
	v_mov_b64_e32 v[52:53], v[36:37]
	v_mov_b64_e32 v[50:51], v[34:35]
	v_mov_b64_e32 v[48:49], v[32:33]
	v_mov_b64_e32 v[18:19], v[34:35]
	v_mov_b64_e32 v[20:21], v[36:37]
	v_mov_b64_e32 v[22:23], v[38:39]
	v_mov_b64_e32 v[24:25], v[40:41]
	v_mov_b64_e32 v[26:27], v[42:43]
	v_mov_b64_e32 v[28:29], v[44:45]
	v_mov_b64_e32 v[30:31], v[46:47]
	v_mov_b64_e32 v[2:3], v[34:35]
	v_mov_b64_e32 v[4:5], v[36:37]
	v_mov_b64_e32 v[6:7], v[38:39]
	v_mov_b64_e32 v[8:9], v[40:41]
	v_mov_b64_e32 v[10:11], v[42:43]
	v_mov_b64_e32 v[12:13], v[44:45]
	v_mov_b64_e32 v[14:15], v[46:47]

; __global__ void __launch_bounds__(NTHR, 2) fwd_mega(Args a) {
;     extern __shared__ __attribute__((aligned(16))) unsigned char lds_raw[];
	.amdhsa_kernel _Z8fwd_mega4Args
		.amdhsa_group_segment_fixed_size 0
		.amdhsa_private_segment_fixed_size 0
		.amdhsa_kernarg_size 536
		.amdhsa_user_sgpr_count 2
		.amdhsa_user_sgpr_dispatch_ptr 0
		.amdhsa_user_sgpr_queue_ptr 0
		.amdhsa_user_sgpr_kernarg_segment_ptr 1
		.amdhsa_user_sgpr_dispatch_id 0
		.amdhsa_user_sgpr_kernarg_preload_length 0
		.amdhsa_user_sgpr_kernarg_preload_offset 0
		.amdhsa_user_sgpr_private_segment_size 0
		.amdhsa_uses_dynamic_stack 0
		.amdhsa_enable_private_segment 0
		.amdhsa_system_sgpr_workgroup_id_x 1
		.amdhsa_system_sgpr_workgroup_id_y 0
		.amdhsa_system_sgpr_workgroup_id_z 0
		.amdhsa_system_sgpr_workgroup_info 0
		.amdhsa_system_vgpr_workitem_id 2
		.amdhsa_next_free_vgpr 256
		.amdhsa_next_free_sgpr 102
		.amdhsa_accum_offset 256
		.amdhsa_reserve_vcc 1
		.amdhsa_float_round_mode_32 0
		.amdhsa_float_round_mode_16_64 0
		.amdhsa_float_denorm_mode_32 3
		.amdhsa_float_denorm_mode_16_64 3
		.amdhsa_dx10_clamp 1
		.amdhsa_ieee_mode 1
		.amdhsa_fp16_overflow 0
		.amdhsa_tg_split 0
		.amdhsa_exception_fp_ieee_invalid_op 0
		.amdhsa_exception_fp_denorm_src 0
		.amdhsa_exception_fp_ieee_div_zero 0
		.amdhsa_exception_fp_ieee_overflow 0
		.amdhsa_exception_fp_ieee_underflow 0
		.amdhsa_exception_fp_ieee_inexact 0
		.amdhsa_exception_int_div_zero 0
	.end_amdhsa_kernel

; __global__ void __launch_bounds__(NTHR, 2) fwd_mega(Args a) {
;     extern __shared__ __attribute__((aligned(16))) unsigned char lds_raw[];
amdhsa.kernels:
  - .agpr_count:     0
    .args:
      - .offset:         0
        .size:           280
        .value_kind:     by_value
      - .offset:         280
        .size:           4
        .value_kind:     hidden_block_count_x
      - .offset:         284
        .size:           4
        .value_kind:     hidden_block_count_y
      - .offset:         288
        .size:           4
        .value_kind:     hidden_block_count_z
      - .offset:         292
        .size:           2
        .value_kind:     hidden_group_size_x
      - .offset:         294
        .size:           2
        .value_kind:     hidden_group_size_y
      - .offset:         296
        .size:           2
        .value_kind:     hidden_group_size_z
      - .offset:         298
        .size:           2
        .value_kind:     hidden_remainder_x
      - .offset:         300
        .size:           2
        .value_kind:     hidden_remainder_y
      - .offset:         302
        .size:           2
        .value_kind:     hidden_remainder_z
      - .offset:         320
        .size:           8
        .value_kind:     hidden_global_offset_x
      - .offset:         328
        .size:           8
        .value_kind:     hidden_global_offset_y
      - .offset:         336
        .size:           8
        .value_kind:     hidden_global_offset_z
      - .offset:         344
        .size:           2
        .value_kind:     hidden_grid_dims
      - .offset:         368
        .size:           8
        .value_kind:     hidden_multigrid_sync_arg
      - .offset:         400
        .size:           4
        .value_kind:     hidden_dynamic_lds_size
    .group_segment_fixed_size: 0
    .kernarg_segment_align: 8
    .kernarg_segment_size: 536
    .language:       OpenCL C
    .language_version:
      - 2
      - 0
    .max_flat_workgroup_size: 512
    .name:           _Z8fwd_mega4Args
    .private_segment_fixed_size: 0
    .sgpr_count:     108
    .sgpr_spill_count: 169
    .symbol:         _Z8fwd_mega4Args.kd
    .uniform_work_group_size: 1
    .uses_dynamic_stack: false
    .vgpr_count:     256
    .vgpr_spill_count: 0
    .wavefront_size: 64
